# K and V^T workspace layouts changed so attention operand loads are contiguous per quad (fresh + cached); PRO silu(cond) staging loads batched; long-branch relays
# speedup vs baseline: 1.0270x; 1.0135x over previous
.LBB0_6:
	s_load_dwordx16 s[12:27], s[0:1], 0x80
	s_lshl_b32 s84, s90, 3
	s_lshl_b32 s64, s90, 9
	s_load_dwordx16 s[48:63], s[0:1], 0x40
	v_mov_b32_e32 v187, 0x358637bd
	s_waitcnt lgkmcnt(0)
	s_add_u32 s6, s26, 0x100000
	s_addc_u32 s7, s27, 0
	s_add_u32 s4, s26, 0x101000
	s_addc_u32 s5, s27, 0
	s_add_u32 s28, s26, 0xbb00000
	s_addc_u32 s29, s27, 0
	s_add_u32 s16, s26, 0x10b00000
	s_addc_u32 s17, s27, 0
	s_add_u32 s18, s26, 0x15b00000
	s_addc_u32 s19, s27, 0
	s_add_u32 s20, s26, 0x17300000
	v_writelane_b32 v251, s4, 21
	s_addc_u32 s21, s27, 0
	v_mbcnt_lo_u32_b32 v2, -1, 0
	v_writelane_b32 v251, s5, 22
	s_add_u32 s4, s26, 0x5800000
	s_addc_u32 s5, s27, 0
	v_writelane_b32 v251, s4, 23
	v_mov_b32_e32 v202, 0x260
	v_mov_b32_e32 v203, 1
	v_writelane_b32 v251, s5, 24
	s_and_b32 s5, s90, 7
	s_cmp_eq_u32 s5, 0
	s_cselect_b64 s[22:23], -1, 0
	s_ashr_i32 s5, s90, 3
	v_writelane_b32 v251, s22, 25
	s_add_u32 s10, s26, 0x6b00000
	s_addc_u32 s11, s27, 0
	v_writelane_b32 v251, s23, 26
	v_writelane_b32 v251, s5, 27
	s_add_u32 s5, s26, 0x1100000
	v_writelane_b32 v251, s5, 28
	s_addc_u32 s5, s27, 0
	s_ashr_i32 s87, s90, 31
	v_writelane_b32 v251, s5, 29
	s_add_u32 s5, s26, 0x16700000
	v_writelane_b32 v251, s5, 30
	s_addc_u32 s5, s27, 0
	s_add_u32 s22, s26, 0x6600000
	v_writelane_b32 v251, s5, 31
	s_addc_u32 s23, s27, 0
	v_writelane_b32 v251, s22, 32
	s_mul_i32 s4, s91, s90
	v_mbcnt_hi_u32_b32 v204, -1, v2
	v_writelane_b32 v251, s23, 33
	s_add_u32 s22, s26, 0xd00000
	s_addc_u32 s23, s27, 0
	v_writelane_b32 v251, s22, 34
	s_add_u32 s5, s26, 0x200000
	v_mov_b32_e32 v205, 0xf149f2ca
	v_writelane_b32 v251, s23, 35
	v_writelane_b32 v251, s5, 36
	s_addc_u32 s5, s27, 0
	v_writelane_b32 v251, s5, 37
	s_add_u32 s5, s24, 0xa000000
	v_writelane_b32 v251, s5, 38
	s_addc_u32 s5, s25, 0
	v_writelane_b32 v251, s5, 39
	s_add_u32 s5, s24, 0xb000000
	v_writelane_b32 v251, s5, 40
	s_addc_u32 s5, s25, 0
	s_add_u32 s96, s26, 0x5300000
	s_addc_u32 s97, s27, 0
	s_add_u32 s74, s26, 0x1e800000
	s_addc_u32 s75, s27, 0
	s_add_u32 s22, s26, 0xc00000
	v_writelane_b32 v251, s5, 41
	s_addc_u32 s23, s27, 0
	v_writelane_b32 v251, s22, 42
	s_add_u32 s5, s26, 0x800000
	v_mov_b64_e32 v[178:179], 0x3bf
	v_writelane_b32 v251, s23, 43
	v_writelane_b32 v251, s5, 44
	s_addc_u32 s5, s27, 0
	v_writelane_b32 v251, s5, 45
	s_add_u32 s5, s26, 0x3d00000
	v_writelane_b32 v251, s5, 46
	s_addc_u32 s5, s27, 0
	v_writelane_b32 v251, s5, 47
	s_load_dword s5, s[0:1], 0xd0
	v_mov_b32_e32 v206, 0xff3
	v_mov_b32_e32 v211, 0x7fc00000
	v_mov_b32_e32 v210, 0x7f800000
	v_not_b32_e32 v250, 63
	s_waitcnt lgkmcnt(0)
	s_mul_i32 s4, s4, s5
	v_writelane_b32 v251, s4, 48
	s_add_u32 s4, s26, 0x6a00000
	s_addc_u32 s5, s27, 0
	s_add_u32 s44, s26, 0x110000
	v_writelane_b32 v251, s4, 49
	s_addc_u32 s45, s27, 0
	v_not_b32_e32 v207, 31
	v_writelane_b32 v251, s5, 50
	s_add_u32 s4, s26, 0x14700000
	s_addc_u32 s5, s27, 0
	v_writelane_b32 v251, s4, 51
	s_bitcmp0_b32 s90, 0
	s_mov_b32 s72, 0x16000
	v_writelane_b32 v251, s5, 52
	s_cselect_b64 s[4:5], -1, 0
	v_writelane_b32 v251, s4, 53
	s_movk_i32 s73, 0x6000
	s_movk_i32 s91, 0x220
	v_writelane_b32 v251, s5, 54
	s_lshr_b32 s4, s90, 1
	v_writelane_b32 v251, s4, 55
	s_add_u32 s4, s26, 0x1e700200
	s_addc_u32 s5, s27, 0
	v_writelane_b32 v251, s4, 56
	s_movk_i32 s82, 0xfefe
	s_mov_b32 s9, 0
	v_writelane_b32 v251, s5, 57
	s_add_u32 s4, s26, 0x1e700400
	s_addc_u32 s5, s27, 0
	v_writelane_b32 v251, s4, 58
	s_nop 1
	v_writelane_b32 v251, s5, 59
	s_add_u32 s4, s26, 0x1e700500
	s_addc_u32 s5, s27, 0
	v_writelane_b32 v251, s4, 60
	s_nop 1
	v_writelane_b32 v251, s5, 61
	s_add_u32 s4, s26, 0x1e700600
	s_addc_u32 s5, s27, 0
	v_writelane_b32 v251, s4, 62
	s_nop 1
	v_writelane_b32 v251, s5, 63
	s_add_u32 s4, s26, 0x1e700700
	s_addc_u32 s5, s27, 0
	v_writelane_b32 v252, s4, 0
	s_nop 1
	v_writelane_b32 v252, s5, 1
	s_add_u32 s4, s26, 0x1e700800
	s_addc_u32 s5, s27, 0
	v_writelane_b32 v252, s4, 2
	s_nop 1
	v_writelane_b32 v252, s5, 3
	s_add_u32 s4, s26, 0x1e700900
	s_addc_u32 s5, s27, 0
	v_writelane_b32 v252, s4, 4
	s_nop 1
	v_writelane_b32 v252, s5, 5
	s_add_u32 s4, s26, 0x1e700a00
	s_addc_u32 s5, s27, 0
	v_writelane_b32 v252, s4, 6
	s_nop 1
	v_writelane_b32 v252, s5, 7
	s_add_u32 s4, s26, 0x1e700b00
	s_addc_u32 s5, s27, 0
	v_writelane_b32 v252, s4, 8
	s_nop 1
	v_writelane_b32 v252, s5, 9
	s_add_u32 s4, s26, 0x1e700c00
	s_addc_u32 s5, s27, 0
	v_writelane_b32 v252, s4, 10
	s_nop 1
	v_writelane_b32 v252, s5, 11
	s_add_u32 s4, s26, 0x1e700d00
	s_addc_u32 s5, s27, 0
	v_writelane_b32 v252, s4, 12
	s_nop 1
	v_writelane_b32 v252, s5, 13
	s_add_u32 s4, s26, 0x1e700e00
	s_addc_u32 s5, s27, 0
	v_writelane_b32 v252, s4, 14
	s_nop 1
	v_writelane_b32 v252, s5, 15
	s_add_u32 s4, s26, 0x1e700f00
	s_addc_u32 s5, s27, 0
	v_writelane_b32 v252, s4, 16
	s_nop 1
	v_writelane_b32 v252, s5, 17
	s_add_u32 s4, s26, 0x1e701000
	s_addc_u32 s5, s27, 0
	v_writelane_b32 v252, s4, 18
	s_nop 1
	v_writelane_b32 v252, s5, 19
	s_add_u32 s4, s26, 0x1e701100
	s_addc_u32 s5, s27, 0
	v_writelane_b32 v252, s4, 20
	s_nop 1
	v_writelane_b32 v252, s5, 21
	s_add_u32 s4, s26, 0x1e701200
	s_addc_u32 s5, s27, 0
	v_writelane_b32 v252, s4, 22
	s_nop 1
	v_writelane_b32 v252, s5, 23
	s_add_u32 s4, s26, 0x1e701300
	s_addc_u32 s5, s27, 0
	v_writelane_b32 v252, s4, 24
	s_cmp_eq_u32 s8, 15
	s_nop 0
	v_writelane_b32 v252, s5, 25
	s_cselect_b64 s[4:5], -1, 0
	v_writelane_b32 v252, s4, 26
	s_cmp_eq_u32 s8, 14
	s_nop 0
	v_writelane_b32 v252, s5, 27
	s_cselect_b64 s[4:5], -1, 0
	v_writelane_b32 v252, s4, 28
	s_cmp_eq_u32 s8, 13
	s_nop 0
	v_writelane_b32 v252, s5, 29
	s_cselect_b64 s[4:5], -1, 0
	v_writelane_b32 v252, s4, 30
	s_cmp_eq_u32 s8, 12
	s_nop 0
	v_writelane_b32 v252, s5, 31
	s_cselect_b64 s[4:5], -1, 0
	v_writelane_b32 v252, s4, 32
	s_cmp_eq_u32 s8, 11
	s_nop 0
	v_writelane_b32 v252, s5, 33
	s_cselect_b64 s[4:5], -1, 0
	v_writelane_b32 v252, s4, 34
	s_cmp_eq_u32 s8, 10
	s_nop 0
	v_writelane_b32 v252, s5, 35
	s_cselect_b64 s[4:5], -1, 0
	v_writelane_b32 v252, s4, 36
	s_cmp_eq_u32 s8, 9
	s_nop 0
	v_writelane_b32 v252, s5, 37
	s_cselect_b64 s[4:5], -1, 0
	v_writelane_b32 v252, s4, 38
	s_cmp_eq_u32 s8, 8
	s_nop 0
	v_writelane_b32 v252, s5, 39
	s_cselect_b64 s[4:5], -1, 0
	v_writelane_b32 v252, s4, 40
	s_cmp_eq_u32 s8, 7
	s_nop 0
	v_writelane_b32 v252, s5, 41
	s_cselect_b64 s[4:5], -1, 0
	v_writelane_b32 v252, s4, 42
	s_cmp_eq_u32 s8, 6
	s_nop 0
	v_writelane_b32 v252, s5, 43
	s_cselect_b64 s[4:5], -1, 0
	v_writelane_b32 v252, s4, 44
	s_cmp_eq_u32 s8, 5
	s_nop 0
	v_writelane_b32 v252, s5, 45
	s_cselect_b64 s[4:5], -1, 0
	v_writelane_b32 v252, s4, 46
	s_cmp_eq_u32 s8, 4
	s_nop 0
	v_writelane_b32 v252, s5, 47
	s_cselect_b64 s[4:5], -1, 0
	v_writelane_b32 v252, s4, 48
	s_cmp_eq_u32 s8, 3
	s_nop 0
	v_writelane_b32 v252, s5, 49
	s_cselect_b64 s[4:5], -1, 0
	v_writelane_b32 v252, s4, 50
	s_cmp_eq_u32 s8, 2
	s_nop 0
	v_writelane_b32 v252, s5, 51
	s_cselect_b64 s[4:5], -1, 0
	v_writelane_b32 v252, s4, 52
	s_cmp_eq_u32 s8, 1
	s_nop 0
	v_writelane_b32 v252, s5, 53
	s_cselect_b64 s[4:5], -1, 0
	v_writelane_b32 v252, s4, 54
	s_cmp_eq_u32 s8, 0
	s_nop 0
	v_writelane_b32 v252, s5, 55
	s_cselect_b64 s[4:5], -1, 0
	v_writelane_b32 v252, s4, 56
	s_nop 1
	v_writelane_b32 v252, s5, 57
	s_lshl_b32 s4, s8, 8
	s_add_u32 s2, s2, s4
	s_addc_u32 s3, s3, 0
	s_add_u32 s4, s2, 0x1400
	s_addc_u32 s5, s3, 0
	v_writelane_b32 v252, s4, 58
	s_add_u32 s2, s2, 0x2400
	s_addc_u32 s3, s3, 0
	v_writelane_b32 v252, s5, 59
	v_writelane_b32 v252, s2, 60
	s_mov_b64 s[4:5], 0x80
	s_nop 0
	v_writelane_b32 v252, s3, 61
	s_add_u32 s2, s26, 0x1e703400
	s_addc_u32 s3, s27, 0
	v_writelane_b32 v252, s2, 62
	s_nop 1
	v_writelane_b32 v252, s3, 63
	s_add_u32 s2, s26, 0x1e703500
	s_addc_u32 s3, s27, 0
	v_writelane_b32 v253, s2, 0
	s_ashr_i32 s85, s84, 31
	s_nop 0
	v_writelane_b32 v253, s3, 1
	s_abs_i32 s2, s90
	v_cvt_f32_u32_e32 v1, s2
	v_writelane_b32 v253, s2, 2
	s_sub_i32 s2, 0, s2
	v_rcp_iflag_f32_e32 v1, v1
	s_nop 0
	v_mul_f32_e32 v1, 0x4f7ffffe, v1
	v_cvt_u32_f32_e32 v1, v1
	s_nop 0
	v_readfirstlane_b32 s3, v1
	s_mul_i32 s2, s2, s3
	s_mul_hi_u32 s2, s3, s2
	s_add_i32 s2, s3, s2
	v_lshrrev_b32_e32 v1, 20, v0
	v_lshrrev_b32_e32 v0, 10, v0
	v_writelane_b32 v253, s2, 3
	v_or_b32_e32 v0, v0, v1
	s_movk_i32 s2, 0x3ff
	v_and_or_b32 v0, v0, s2, v183
	s_lshl_b64 s[2:3], s[84:85], 11
	v_writelane_b32 v253, s2, 4
	v_mov_b32_e32 v1, 0
	s_nop 0
	v_writelane_b32 v253, s3, 5
	s_add_u32 s2, s48, 0xb4000
	v_writelane_b32 v253, s48, 6
	s_addc_u32 s3, s49, 0
	s_ashr_i32 s65, s64, 31
	v_writelane_b32 v253, s49, 7
	v_writelane_b32 v253, s50, 8
	v_writelane_b32 v253, s51, 9
	v_writelane_b32 v253, s52, 10
	v_writelane_b32 v253, s53, 11
	v_writelane_b32 v253, s54, 12
	v_writelane_b32 v253, s55, 13
	v_writelane_b32 v253, s56, 14
	v_writelane_b32 v253, s57, 15
	v_writelane_b32 v253, s58, 16
	v_writelane_b32 v253, s59, 17
	v_writelane_b32 v253, s60, 18
	v_writelane_b32 v253, s61, 19
	v_writelane_b32 v253, s62, 20
	v_writelane_b32 v253, s63, 21
	s_load_dwordx16 s[48:63], s[0:1], 0x0
	v_writelane_b32 v253, s2, 22
	s_lshl_b32 s93, s90, 6
	s_lshl_b32 s92, s90, 8
	v_writelane_b32 v253, s3, 23
	s_lshl_b32 s12, s90, 4
	s_lshl_b32 s13, s90, 12
	s_lshl_b64 s[14:15], s[64:65], 4
	s_lshl_b64 s[36:37], s[64:65], 2
	s_waitcnt lgkmcnt(0)
	s_add_u32 s0, s52, 16
	v_writelane_b32 v253, s48, 24
	s_addc_u32 s1, s53, 0
	s_lshl_b64 s[80:81], s[64:65], 5
	v_writelane_b32 v253, s49, 25
	v_writelane_b32 v253, s50, 26
	v_writelane_b32 v253, s51, 27
	v_writelane_b32 v253, s52, 28
	v_writelane_b32 v253, s53, 29
	v_writelane_b32 v253, s54, 30
	v_writelane_b32 v253, s55, 31
	v_writelane_b32 v253, s56, 32
	v_writelane_b32 v253, s57, 33
	v_writelane_b32 v253, s58, 34
	v_writelane_b32 v253, s59, 35
	v_writelane_b32 v253, s60, 36
	v_writelane_b32 v253, s61, 37
	v_writelane_b32 v253, s62, 38
	v_writelane_b32 v253, s63, 39
	v_writelane_b32 v253, s0, 40
	v_writelane_b32 v254, s80, 0
	s_mov_b64 s[54:55], s[10:11]
	v_writelane_b32 v253, s1, 41
	s_add_i32 s0, 0, 0x20000
	v_writelane_b32 v253, s0, 42
	s_add_i32 s0, 0, 0x22000
	v_writelane_b32 v253, s0, 43
	s_add_i32 s0, 0, 0x22004
	v_writelane_b32 v253, s0, 44
	v_writelane_b32 v254, s81, 1
	v_cmp_eq_u32_e64 s[0:1], 0, v0
	v_writelane_b32 v254, s18, 2
	s_movk_i32 s10, 0x1000
	v_writelane_b32 v253, s0, 45
	v_writelane_b32 v254, s19, 3
	v_writelane_b32 v254, s20, 4
	v_writelane_b32 v253, s1, 46
	s_mov_b32 s0, s84
	v_writelane_b32 v253, s0, 47
	v_writelane_b32 v254, s21, 5
	v_writelane_b32 v254, s96, 6
	v_writelane_b32 v253, s1, 48
	s_mov_b32 s0, s64
	v_writelane_b32 v253, s0, 49
	v_writelane_b32 v254, s97, 7
	v_writelane_b32 v254, s44, 8
	v_writelane_b32 v253, s1, 50
	v_writelane_b32 v253, s6, 51
	v_writelane_b32 v254, s45, 9
	v_writelane_b32 v254, s12, 10
	v_writelane_b32 v253, s7, 52
	v_writelane_b32 v253, s28, 53
	v_writelane_b32 v254, s13, 11
	v_writelane_b32 v254, s14, 12
	v_writelane_b32 v253, s29, 54
	v_writelane_b32 v253, s16, 55
	v_writelane_b32 v254, s15, 13
	v_writelane_b32 v254, s36, 14
	v_writelane_b32 v253, s17, 56
	v_writelane_b32 v253, s87, 57
	v_writelane_b32 v253, s74, 58
	s_movk_i32 s11, 0xff
	s_mov_b32 s3, 0xf800000
	v_writelane_b32 v253, s75, 59
	v_writelane_b32 v253, s93, 60
	v_writelane_b32 v253, s92, 61
	v_writelane_b32 v253, s54, 62
	s_mov_b32 s2, s88
	v_writelane_b32 v254, s37, 15
	v_writelane_b32 v253, s55, 63
	s_branch .LBB0_11
.Lrelay_end:
	s_endpgm
.LBB0_7:
	buffer_inv sc1

.LBB0_624:
	s_and_b32 s39, s29, 3
	s_add_u32 s30, s46, s70
	v_mov_b32_e32 v157, v1
	s_addc_u32 s31, s47, s71
	v_mov_b32_e32 v161, v1
	s_add_i32 m0, s33, 0x18000
	v_lshl_add_u64 v[6:7], s[30:31], 0, v[156:157]
	s_waitcnt vmcnt(2)
	s_barrier
	global_load_lds_dwordx4 v[6:7], off
	v_lshl_add_u64 v[6:7], s[30:31], 0, v[160:161]
	s_add_i32 m0, s33, 0x1a000
	s_add_i32 s84, s33, 0x8000
	s_add_i32 s85, s33, 0xa000
	global_load_lds_dwordx4 v[6:7], off
	v_lshl_add_u64 v[2:3], v[2:3], 0, s[4:5]
	s_mov_b32 m0, s84
	s_add_u32 s0, s0, s70
	global_load_lds_dwordx4 v[2:3], off
	v_lshl_add_u64 v[2:3], v[4:5], 0, s[4:5]
	s_mov_b32 m0, s85
	s_addc_u32 s1, s1, s71
	global_load_lds_dwordx4 v[2:3], off
	s_add_i32 m0, s33, 0x1c000
	v_lshl_add_u64 v[2:3], s[0:1], 0, v[156:157]
	global_load_lds_dwordx4 v[2:3], off
	v_lshl_add_u64 v[2:3], s[0:1], 0, v[160:161]
	s_add_i32 m0, s33, 0x1e000
	s_add_i32 s75, s74, -2
	global_load_lds_dwordx4 v[2:3], off
	s_cmpk_lt_u32 s24, 0x100
	s_cselect_b64 s[0:1], -1, 0
	v_writelane_b32 v254, s0, 60
	s_waitcnt vmcnt(6)
	v_writelane_b32 v255, s36, 1
	v_lshl_or_b32 v0, s19, 13, v181
	v_writelane_b32 v254, s1, 61
	v_lshl_or_b32 v104, s39, 12, v181
	v_readlane_b32 s0, v254, 36
	s_lshr_b32 s0, s0, 1
	v_writelane_b32 v255, s37, 2
	v_writelane_b32 v254, s0, 48
	v_lshl_add_u64 v[90:91], s[66:67], 0, v[154:155]
	v_readlane_b32 s0, v254, 30
	v_readlane_b32 s1, v254, 31
	s_cmp_lg_u64 s[0:1], 0
	s_cselect_b64 s[68:69], -1, 0
	s_cmp_lg_u64 s[78:79], 0
	s_cselect_b64 s[76:77], -1, 0
	s_cmp_lg_u64 s[36:37], 0
	s_cselect_b64 s[92:93], -1, 0
	s_cmp_lg_u64 s[62:63], 0
	s_cselect_b64 s[94:95], -1, 0
	s_lshl_b64 s[96:97], s[70:71], 1
	v_lshl_add_u64 v[92:93], s[66:67], 0, v[158:159]
	s_mov_b32 s29, 0
	v_add_u32_e32 v105, 0, v0
	s_barrier
	s_branch .LBB0_627
.Lrelay_7:
	s_branch .LBB0_7
.Lrelay_8:
	s_branch .LBB0_8
.Lrelay_9:
	s_branch .LBB0_9
.LBB0_625:
	s_mov_b64 s[0:1], 0

.LBB0_826:
	v_readlane_b32 s18, v254, 2
	v_readlane_b32 s20, v254, 4
	v_readlane_b32 s96, v254, 6
	s_mov_b32 s86, s36
	s_and_b64 vcc, exec, s[0:1]
	v_readlane_b32 s19, v254, 3
	v_readlane_b32 s21, v254, 5
	v_readlane_b32 s97, v254, 7
	s_cbranch_vccz .LBB0_851
	v_readlane_b32 s0, v254, 17
	s_cmpk_gt_i32 s0, 0x4ff
	s_cbranch_scc1 .LBB0_851
	v_readlane_b32 s36, v253, 6
	s_lshl_b32 s0, s76, 6
	v_readlane_b32 s46, v253, 16
	v_readlane_b32 s47, v253, 17
	s_add_u32 s0, s46, s0
	v_readlane_b32 s2, v254, 16
	s_addc_u32 s1, s47, 0
	s_bfe_u32 s28, s2, 0x20006
	v_readlane_b32 s2, v254, 18
	v_and_b32_e32 v4, 64, v204
	s_lshl_b32 s29, s2, 4
	v_cmp_gt_u32_e32 vcc, 32, v182
	v_xor_b32_e32 v3, 32, v204
	v_add_u32_e32 v4, 64, v4
	v_and_b32_e32 v181, 31, v184
	s_andn2_b32 s29, s29, 63
	v_cndmask_b32_e64 v185, 0, 1.0, vcc
	v_cmp_lt_i32_e32 vcc, v3, v4
	v_lshrrev_b32_e32 v2, 5, v182
	v_lshlrev_b32_e32 v0, 10, v181
	v_cndmask_b32_e32 v3, v204, v3, vcc
	s_add_i32 s8, s29, 0xffffff64
	v_lshlrev_b32_e32 v186, 3, v2
	v_lshlrev_b32_e32 v2, 2, v2
	v_lshlrev_b32_e32 v217, 2, v3
	v_or_b32_e32 v4, 0x8000, v0
	v_add_u32_e32 v3, s8, v181
	v_add_u32_e32 v218, 0x100, v181
	v_sub_u32_e32 v219, v3, v2
	v_lshlrev_b32_e32 v188, 1, v2
	v_lshlrev_b32_e32 v190, 1, v0
	v_lshlrev_b32_e32 v192, 1, v4
	v_lshrrev_b32_e32 v232, 2, v181
	v_and_b32_e32 v233, 3, v181
	v_lshlrev_b32_e32 v232, 11, v232
	v_lshl_or_b32 v232, v233, 4, v232
	v_lshl_or_b32 v232, v186, 3, v232
	v_mov_b32_e32 v233, 0
	v_readlane_b32 s33, v254, 17
	v_readlane_b32 s37, v253, 7
	v_readlane_b32 s38, v253, 8
	v_readlane_b32 s39, v253, 9
	v_readlane_b32 s40, v253, 10
	v_readlane_b32 s41, v253, 11
	v_readlane_b32 s42, v253, 12
	v_readlane_b32 s43, v253, 13
	v_readlane_b32 s44, v253, 14
	v_readlane_b32 s45, v253, 15
	v_readlane_b32 s48, v253, 18
	v_readlane_b32 s49, v253, 19
	v_readlane_b32 s50, v253, 20
	v_readlane_b32 s51, v253, 21
	s_branch .LBB0_830

.LBB0_832:
	s_andn2_b64 vcc, exec, s[24:25]
	s_cbranch_vccnz .LBB0_834
	s_ashr_i32 s8, s33, 7
	s_lshl_b32 s24, s8, 12
	s_lshr_b32 s30, s33, 5
	s_and_b32 s27, s33, 31
	s_add_i32 s26, s24, 0x2000
	s_movk_i32 s40, 0x1000
	s_movk_i32 s34, 16
	s_branch .LBB0_835
.LBB0_834:
	s_movk_i32 s40, 0x100
	s_movk_i32 s34, 16
.LBB0_835:
	s_and_b32 s35, s30, 3
	s_lshl_b32 s31, s27, 7
	s_lshl_b32 s24, s35, 2
	s_add_i32 s41, s31, s29
	s_mov_b32 s100, s41
	s_or_b32 s30, s24, s28
	s_add_i32 s24, s41, s26
	s_ashr_i32 s25, s24, 31
	s_lshl_b64 s[24:25], s[24:25], 11
	s_add_u32 s24, s16, s24
	s_addc_u32 s25, s17, s25
	s_lshl_b32 s27, s30, 7
	s_add_u32 s24, s24, s27
	s_addc_u32 s25, s25, 0
	v_lshlrev_b32_e32 v194, 1, v186
	v_mov_b32_e32 v195, v1
	v_lshl_add_u64 v[2:3], s[24:25], 0, v[194:195]
	v_mov_b32_e32 v191, v1
	v_lshl_add_u64 v[4:5], v[2:3], 0, v[190:191]
	global_load_dwordx4 v[98:101], v[4:5], off
	global_load_dwordx4 v[102:105], v[4:5], off offset:32
	global_load_dwordx4 v[106:109], v[4:5], off offset:64
	global_load_dwordx4 v[110:113], v[4:5], off offset:96
	s_lshl_b32 s27, s30, 2
	v_mov_b32_e32 v193, v1
	v_mov_b32_e32 v0, s27
	v_lshl_add_u64 v[2:3], v[2:3], 0, v[192:193]
	global_load_dword v16, v0, s[0:1]
	global_load_dwordx4 v[114:117], v[2:3], off
	global_load_dwordx4 v[118:121], v[2:3], off offset:32
	global_load_dwordx4 v[122:125], v[2:3], off offset:64
	global_load_dwordx4 v[126:129], v[2:3], off offset:96
	s_mul_i32 s42, s8, 0x12000
	s_mul_hi_i32 s43, s8, 0x12000
	s_mul_hi_i32 s44, s8, 0x104000
	s_mul_i32 s45, s8, 0x104000
	s_lshl_b32 s8, s8, 1
	s_add_i32 s8, s8, s76
	s_mul_i32 s30, s8, 0x40000
	v_add_u32_e32 v189, s31, v219
	s_mul_hi_i32 s31, s8, 0x40000
	s_add_u32 s30, s96, s30
	s_addc_u32 s31, s97, s31
	s_lshl_b32 s8, s8, 18
	s_lshl_b32 s47, s35, 11
	s_lshl_b32 s46, s35, 6
	s_add_i32 s8, s8, s47
	s_mov_b32 s35, 0
	s_mul_i32 s47, s46, s34
	s_add_u32 s34, s74, s8
	s_mul_i32 s38, s26, 0x200
	s_addc_u32 s35, s75, s35
	s_mul_hi_i32 s39, s26, 0x200
	s_add_u32 s38, s18, s38
	s_addc_u32 s39, s19, s39
	s_add_u32 s8, s45, 0x240000
	s_addc_u32 s44, s44, 0
	s_lshl_b32 s45, s47, 1
	s_add_u32 s45, s20, s45
	s_addc_u32 s47, s21, 0
	s_add_i32 s48, s41, 0xc0
	s_max_i32 s51, s41, 0x80
	s_min_i32 s50, s48, s40
	s_addk_i32 s51, 0xff80
	s_and_b64 s[40:41], s[22:23], exec
	v_mov_b32_e32 v14, v1
	v_mov_b32_e32 v15, v1
	s_cselect_b32 s41, s44, s43
	s_cselect_b32 s40, s8, s42
	v_mov_b32_e32 v0, v1
	v_mov_b32_e32 v2, v1
	v_mov_b32_e32 v3, v1
	v_mov_b32_e32 v4, v1
	v_mov_b32_e32 v5, v1
	v_mov_b32_e32 v6, v1
	v_mov_b32_e32 v7, v1
	v_mov_b32_e32 v8, v1
	v_mov_b32_e32 v9, v1
	v_mov_b32_e32 v10, v1
	v_mov_b32_e32 v11, v1
	v_mov_b32_e32 v12, v1
	v_mov_b32_e32 v13, v1
	v_mov_b64_e32 v[64:65], v[14:15]
	v_mov_b64_e32 v[48:49], v[14:15]
	s_waitcnt lgkmcnt(0)
	v_mov_b64_e32 v[32:33], v[14:15]
	s_lshl_b64 s[40:41], s[40:41], 1
	v_mov_b64_e32 v[62:63], v[12:13]
	v_mov_b64_e32 v[60:61], v[10:11]
	v_mov_b64_e32 v[58:59], v[8:9]
	v_mov_b64_e32 v[56:57], v[6:7]
	v_mov_b64_e32 v[54:55], v[4:5]
	v_mov_b64_e32 v[52:53], v[2:3]
	v_mov_b64_e32 v[50:51], v[0:1]
	v_mov_b64_e32 v[46:47], v[12:13]
	v_mov_b64_e32 v[44:45], v[10:11]
	v_mov_b64_e32 v[42:43], v[8:9]
	v_mov_b64_e32 v[40:41], v[6:7]
	v_mov_b64_e32 v[38:39], v[4:5]
	v_mov_b64_e32 v[36:37], v[2:3]
	v_mov_b64_e32 v[34:35], v[0:1]
	v_mov_b64_e32 v[30:31], v[12:13]
	v_mov_b64_e32 v[28:29], v[10:11]
	v_mov_b64_e32 v[26:27], v[8:9]
	v_mov_b64_e32 v[24:25], v[6:7]
	v_mov_b64_e32 v[22:23], v[4:5]
	v_mov_b64_e32 v[20:21], v[2:3]
	v_mov_b64_e32 v[18:19], v[0:1]
	s_add_u32 s40, s45, s40
	s_waitcnt vmcnt(0)
	v_mul_f32_e32 v191, 0x3fb8aa3b, v16
	v_mov_b64_e32 v[16:17], v[14:15]
	s_mov_b64 s[26:27], -1
	v_mov_b32_e32 v220, v185
	s_addc_u32 s41, s47, s41
	s_lshl_b32 s52, s46, 3
	v_mov_b32_e32 v193, v185
	v_mov_b32_e32 v221, v191
	v_mov_b64_e32 v[14:15], v[12:13]
	v_mov_b64_e32 v[12:13], v[10:11]
	v_mov_b64_e32 v[10:11], v[8:9]
	v_mov_b64_e32 v[8:9], v[6:7]
	v_mov_b64_e32 v[6:7], v[4:5]
	v_mov_b64_e32 v[4:5], v[2:3]
	v_mov_b64_e32 v[2:3], v[0:1]
	s_branch .LBB0_837

.LBB0_837:
	s_andn2_b64 vcc, exec, s[26:27]
	s_cbranch_vccnz .LBB0_840
	s_andn2_b64 vcc, exec, s[22:23]
	s_cbranch_vccnz .LBB0_841
	s_movk_i32 s8, 16
	s_mov_b64 s[42:43], -1
	s_mov_b32 s53, s50
	s_mov_b32 s44, s51
	s_mov_b64 s[48:49], s[38:39]
	s_mov_b64 s[46:47], s[40:41]
	s_cmp_ge_i32 s44, s53
	s_cbranch_scc1 .LBB0_836
	s_branch .LBB0_842
.LBB0_840:
	s_mov_b64 s[42:43], 0
	s_movk_i32 s53, 0x200
	s_mov_b32 s44, 0
	s_movk_i32 s8, 16
	s_mov_b64 s[48:49], s[30:31]
	s_mov_b64 s[46:47], s[34:35]
	s_cmp_ge_i32 s44, s53
	s_cbranch_scc0 .LBB0_842
	s_branch .LBB0_836
.LBB0_841:
	s_movk_i32 s8, 16
	s_mov_b32 s44, 0
	s_movk_i32 s53, 0x100
	s_mov_b64 s[42:43], 0
	s_mov_b64 s[48:49], s[38:39]
	s_mov_b64 s[46:47], s[40:41]
	s_cmp_ge_i32 s44, s53
	s_cbranch_scc1 .LBB0_836
.LBB0_842:
	s_mov_b32 s45, s9
	s_lshl_b64 s[56:57], s[44:45], 9
	s_add_u32 s56, s46, s56
	v_mul_u32_u24_e32 v68, s8, v218
	s_addc_u32 s57, s47, s57
	v_mov_b32_e32 v195, v1
	v_mul_u32_u24_e32 v66, s8, v181
	v_lshl_add_u64 v[70:71], s[56:57], 0, v[194:195]
	v_lshlrev_b32_e32 v0, 1, v68
	v_lshl_add_u64 v[72:73], v[70:71], 0, v[0:1]
	v_lshlrev_b32_e32 v0, 1, v66
	s_add_u32 s48, s48, s52
	v_lshl_add_u64 v[70:71], v[70:71], 0, v[0:1]
	s_addc_u32 s49, s49, 0
	global_load_dwordx4 v[130:133], v[72:73], off offset:1024
	global_load_dwordx4 v[138:141], v[70:71], off offset:1024
	global_load_dwordx4 v[154:157], v[72:73], off
	global_load_dwordx4 v[158:161], v[70:71], off
	s_lshl_b64 s[56:57], s[44:45], 9
	s_add_u32 s56, s56, s48
	s_addc_u32 s57, s57, s49
	v_lshl_add_u64 v[70:71], s[56:57], 0, v[232:233]
	global_load_dwordx4 v[134:137], v[70:71], off offset:384
	global_load_dwordx4 v[142:145], v[70:71], off offset:256
	global_load_dwordx4 v[146:149], v[70:71], off offset:128
	global_load_dwordx4 v[150:153], v[70:71], off
	v_lshl_add_u64 v[196:197], s[46:47], 0, v[194:195]
	v_lshl_add_u64 v[198:199], s[48:49], 0, v[232:233]
	v_subrev_u32_e32 v195, s44, v189
	v_lshlrev_b32_e32 v0, 1, v66
	v_lshlrev_b32_e32 v200, 1, v68
.LBB0_843:
	s_waitcnt vmcnt(0)
	v_mfma_f32_32x32x16_bf16 v[82:97], v[150:153], v[98:101], 0
	s_mov_b32 s8, s44
	s_add_i32 s44, s44, 32
	s_cmp_ge_i32 s44, s53
	s_cselect_b64 s[46:47], -1, 0
	s_cmp_lt_i32 s44, s53
	v_mov_b64_e32 v[224:225], v[136:137]
	s_cselect_b32 s8, s44, s8
	v_mfma_f32_32x32x16_bf16 v[66:81], v[150:153], v[114:117], 0
	v_mov_b64_e32 v[222:223], v[134:135]
	s_lshl_b64 vcc, s[8:9], 9
	v_lshl_add_u64 v[134:135], vcc, 0, v[196:197]
	v_mov_b32_e32 v201, v1
	v_lshl_add_u64 v[136:137], v[134:135], 0, v[0:1]
	v_lshl_add_u64 v[134:135], v[134:135], 0, v[200:201]
	global_load_dwordx4 v[162:165], v[136:137], off
	global_load_dwordx4 v[166:169], v[134:135], off
	global_load_dwordx4 v[170:173], v[136:137], off offset:1024
	global_load_dwordx4 v[174:177], v[134:135], off offset:1024
	v_mfma_f32_32x32x16_bf16 v[82:97], v[146:149], v[102:105], v[82:97]
	v_lshl_add_u64 v[134:135], vcc, 0, v[198:199]
	s_andn2_b64 vcc, exec, s[42:43]
	v_mfma_f32_32x32x16_bf16 v[66:81], v[146:149], v[118:121], v[66:81]
	global_load_dwordx4 v[150:153], v[134:135], off
	global_load_dwordx4 v[146:149], v[134:135], off offset:128
	v_mfma_f32_32x32x16_bf16 v[82:97], v[142:145], v[106:109], v[82:97]
	v_mfma_f32_32x32x16_bf16 v[66:81], v[142:145], v[122:125], v[66:81]
	global_load_dwordx4 v[142:145], v[134:135], off offset:256
	s_nop 0
	global_load_dwordx4 v[134:137], v[134:135], off offset:384
	v_mfma_f32_32x32x16_bf16 v[82:97], v[222:225], v[110:113], v[82:97]
	v_mfma_f32_32x32x16_bf16 v[66:81], v[222:225], v[126:129], v[66:81]
	s_sub_i32 s101, s44, s100
	s_add_i32 s101, s101, 32
	s_cmp_le_u32 s101, 0xa0
	s_cbranch_scc1 .LBB0_845
	s_cbranch_vccnz .LBB0_845
	v_add_u32_e32 v201, 27, v195
	s_movk_i32 s8, 0xfeff
	v_cmp_gt_u32_e32 vcc, s8, v201
	v_add_u32_e32 v201, 26, v195
	s_nop 5
	v_cndmask_b32_e32 v82, v82, v205, vcc
	v_cmp_lt_u32_e32 vcc, s82, v201
	v_add_u32_e32 v201, 25, v195
	s_nop 0
	v_cndmask_b32_e32 v83, v205, v83, vcc
	v_cmp_lt_u32_e32 vcc, s82, v201
	v_add_u32_e32 v201, 24, v195
	s_nop 0
	v_cndmask_b32_e32 v84, v205, v84, vcc
	v_cmp_lt_u32_e32 vcc, s82, v201
	v_add_u32_e32 v201, 19, v195
	s_nop 0
	v_cndmask_b32_e32 v85, v205, v85, vcc
	v_cmp_lt_u32_e32 vcc, s82, v201
	v_add_u32_e32 v201, 18, v195
	s_nop 0
	v_cndmask_b32_e32 v86, v205, v86, vcc
	v_cmp_lt_u32_e32 vcc, s82, v201
	v_add_u32_e32 v201, 17, v195
	s_nop 0
	v_cndmask_b32_e32 v87, v205, v87, vcc
	v_cmp_lt_u32_e32 vcc, s82, v201
	v_add_u32_e32 v201, 16, v195
	s_nop 0
	v_cndmask_b32_e32 v88, v205, v88, vcc
	v_cmp_lt_u32_e32 vcc, s82, v201
	v_add_u32_e32 v201, 11, v195
	s_nop 0
	v_cndmask_b32_e32 v89, v205, v89, vcc
	v_cmp_lt_u32_e32 vcc, s82, v201
	v_add_u32_e32 v201, 10, v195
	s_nop 0
	v_cndmask_b32_e32 v90, v205, v90, vcc
	v_cmp_lt_u32_e32 vcc, s82, v201
	v_add_u32_e32 v201, 9, v195
	s_nop 0
	v_cndmask_b32_e32 v91, v205, v91, vcc
	v_cmp_lt_u32_e32 vcc, s82, v201
	v_add_u32_e32 v201, 8, v195
	s_nop 0
	v_cndmask_b32_e32 v92, v205, v92, vcc
	v_cmp_lt_u32_e32 vcc, s82, v201
	v_add_u32_e32 v201, 3, v195
	s_nop 0
	v_cndmask_b32_e32 v93, v205, v93, vcc
	v_cmp_lt_u32_e32 vcc, s82, v201
	v_add_u32_e32 v201, 2, v195
	s_nop 0
	v_cndmask_b32_e32 v94, v205, v94, vcc
	v_cmp_lt_u32_e32 vcc, s82, v201
	v_add_u32_e32 v201, 1, v195
	s_nop 0
	v_cndmask_b32_e32 v95, v205, v95, vcc
	v_cmp_lt_u32_e32 vcc, s82, v201
	v_add_u32_e32 v201, 59, v195
	s_nop 0
	v_cndmask_b32_e32 v96, v205, v96, vcc
	v_cmp_lt_u32_e32 vcc, s82, v195
	s_nop 1
	v_cndmask_b32_e32 v97, v205, v97, vcc
	v_cmp_lt_u32_e32 vcc, s82, v201
	v_add_u32_e32 v201, 58, v195
	s_nop 0
	v_cndmask_b32_e32 v66, v205, v66, vcc
	v_cmp_lt_u32_e32 vcc, s82, v201
	v_add_u32_e32 v201, 57, v195
	s_nop 0
	v_cndmask_b32_e32 v67, v205, v67, vcc
	v_cmp_lt_u32_e32 vcc, s82, v201
	v_add_u32_e32 v201, 56, v195
	s_nop 0
	v_cndmask_b32_e32 v68, v205, v68, vcc
	v_cmp_lt_u32_e32 vcc, s82, v201
	v_add_u32_e32 v201, 51, v195
	s_nop 0
	v_cndmask_b32_e32 v69, v205, v69, vcc
	v_cmp_lt_u32_e32 vcc, s82, v201
	v_add_u32_e32 v201, 50, v195
	s_nop 0
	v_cndmask_b32_e32 v70, v205, v70, vcc
	v_cmp_lt_u32_e32 vcc, s82, v201
	v_add_u32_e32 v201, 49, v195
	s_nop 0
	v_cndmask_b32_e32 v71, v205, v71, vcc
	v_cmp_lt_u32_e32 vcc, s82, v201
	v_add_u32_e32 v201, 48, v195
	s_nop 0
	v_cndmask_b32_e32 v72, v205, v72, vcc
	v_cmp_lt_u32_e32 vcc, s82, v201
	v_add_u32_e32 v201, 43, v195
	s_nop 0
	v_cndmask_b32_e32 v73, v205, v73, vcc
	v_cmp_lt_u32_e32 vcc, s82, v201
	v_add_u32_e32 v201, 42, v195
	s_nop 0
	v_cndmask_b32_e32 v74, v205, v74, vcc
	v_cmp_lt_u32_e32 vcc, s82, v201
	v_add_u32_e32 v201, 41, v195
	s_nop 0
	v_cndmask_b32_e32 v75, v205, v75, vcc
	v_cmp_lt_u32_e32 vcc, s82, v201
	v_add_u32_e32 v201, 40, v195
	s_nop 0
	v_cndmask_b32_e32 v76, v205, v76, vcc
	v_cmp_lt_u32_e32 vcc, s82, v201
	v_add_u32_e32 v201, 35, v195
	s_nop 0
	v_cndmask_b32_e32 v77, v205, v77, vcc
	v_cmp_lt_u32_e32 vcc, s82, v201
	v_add_u32_e32 v201, 34, v195
	s_nop 0
	v_cndmask_b32_e32 v78, v205, v78, vcc
	v_cmp_lt_u32_e32 vcc, s82, v201
	v_add_u32_e32 v201, 33, v195
	s_nop 0
	v_cndmask_b32_e32 v79, v205, v79, vcc
	v_cmp_lt_u32_e32 vcc, s82, v201
	v_add_u32_e32 v201, 32, v195
	s_nop 0
	v_cndmask_b32_e32 v80, v205, v80, vcc
	v_cmp_lt_u32_e32 vcc, s82, v201
	s_nop 1
	v_cndmask_b32_e32 v81, v205, v81, vcc

.LBB0_878:
	v_ashrrev_i32_e32 v165, 31, v164
	s_mov_b64 s[26:27], -1
	s_and_b64 vcc, exec, s[30:31]
	s_cbranch_vccz .LBB0_880
	v_mov_b64_e32 v[168:169], s[18:19]
	v_lshrrev_b32_e32 v244, 2, v164
	v_and_b32_e32 v245, 3, v164
	v_lshlrev_b32_e32 v244, 11, v244
	v_lshl_or_b32 v244, v245, 4, v244
	v_lshrrev_b32_e32 v245, 3, v158
	v_mul_u32_u24_e32 v245, 48, v245
	v_add_u32_e32 v244, v244, v245
	v_mov_b32_e32 v245, 0
	v_lshl_add_u64 v[168:169], v[168:169], 0, v[244:245]
	v_lshl_add_u64 v[168:169], s[62:63], 3, v[168:169]
	s_mov_b64 s[100:101], 0x60
	s_mov_b64 s[26:27], 0
.LBB0_880:
	s_lshl_b32 s8, s22, 8
	s_add_i32 s64, s62, s8
	s_andn2_b64 vcc, exec, s[26:27]
	s_ashr_i32 s65, s64, 31
	s_cbranch_vccnz .LBB0_882
	v_lshlrev_b64 v[168:169], 11, v[164:165]
	v_lshl_add_u64 v[168:169], s[16:17], 0, v[168:169]
	s_mov_b32 s6, 0x3e38aa3b
	v_lshl_add_u64 v[168:169], s[64:65], 1, v[168:169]
	s_mov_b64 s[100:101], 0
	v_pk_mul_f32 v[144:145], v[144:145], s[6:7] op_sel_hi:[1,0]
	v_pk_mul_f32 v[142:143], v[142:143], s[6:7] op_sel_hi:[1,0]
	v_pk_mul_f32 v[140:141], v[140:141], s[6:7] op_sel_hi:[1,0]
	v_pk_mul_f32 v[138:139], v[138:139], s[6:7] op_sel_hi:[1,0]
	v_pk_mul_f32 v[136:137], v[136:137], s[6:7] op_sel_hi:[1,0]
	v_pk_mul_f32 v[134:135], v[134:135], s[6:7] op_sel_hi:[1,0]
	v_pk_mul_f32 v[132:133], v[132:133], s[6:7] op_sel_hi:[1,0]
	v_pk_mul_f32 v[130:131], v[130:131], s[6:7] op_sel_hi:[1,0]
.LBB0_882:
	v_lshl_add_u64 v[168:169], v[158:159], 1, v[168:169]
	v_lshl_add_u64 v[238:239], v[168:169], 0, s[100:101]
	v_lshl_add_u64 v[240:241], v[238:239], 0, s[100:101]
	v_lshl_add_u64 v[242:243], v[240:241], 0, s[100:101]
	v_cvt_pk_bf16_f32 v130, v130, v131
	v_cvt_pk_bf16_f32 v131, v132, v133
	v_cvt_pk_bf16_f32 v134, v134, v135
	v_cvt_pk_bf16_f32 v135, v136, v137
	global_store_dwordx2 v[242:243], v[130:131], off offset:96
	v_pk_mul_f32 v[130:131], v[128:129], v[128:129]
	v_pk_mul_f32 v[132:133], v[126:127], v[126:127]
	global_store_dwordx2 v[240:241], v[134:135], off offset:64
	v_pk_mov_b32 v[134:135], v[132:133], v[130:131] op_sel:[1,0]
	v_mov_b32_e32 v133, v131
	v_pk_add_f32 v[130:131], v[134:135], v[132:133]
	v_pk_mul_f32 v[132:133], v[124:125], v[124:125]
	v_pk_mul_f32 v[134:135], v[122:123], v[122:123]
	v_mul_f32_e32 v0, v114, v114
	v_pk_mov_b32 v[136:137], v[134:135], v[132:133] op_sel:[1,0]
	v_mov_b32_e32 v135, v133
	v_pk_add_f32 v[132:133], v[136:137], v[134:135]
	v_mul_f32_e32 v134, v115, v115
	v_pk_add_f32 v[130:131], v[130:131], v[130:131] op_sel:[0,1] op_sel_hi:[1,0]
	v_pk_add_f32 v[132:133], v[132:133], v[132:133] op_sel:[0,1] op_sel_hi:[1,0]
	v_mov_b32_e32 v131, v0
	v_mov_b32_e32 v133, v134
	v_mul_f32_e32 v0, v119, v119
	v_mul_f32_e32 v135, v116, v116
	v_pk_add_f32 v[130:131], v[130:131], v[132:133]
	v_pk_fma_f32 v[132:133], v[118:119], v[118:119], v[0:1] op_sel_hi:[1,1,0]
	v_mul_f32_e32 v0, v121, v121
	v_mul_f32_e32 v136, v117, v117
	v_mov_b32_e32 v133, v135
	v_pk_fma_f32 v[134:135], v[120:121], v[120:121], v[0:1] op_sel_hi:[1,1,0]
	s_xor_b64 s[22:23], s[0:1], -1
	v_mov_b32_e32 v135, v136
	v_pk_add_f32 v[132:133], v[132:133], v[134:135]
	v_cvt_pk_bf16_f32 v142, v142, v143
	v_pk_add_f32 v[130:131], v[130:131], v[132:133]
	v_cvt_pk_bf16_f32 v143, v144, v145
	v_add_f32_e32 v0, v130, v131
	ds_bpermute_b32 v130, v174, v0
	v_cvt_pk_bf16_f32 v138, v138, v139
	v_cvt_pk_bf16_f32 v139, v140, v141
	global_store_dwordx2 v[168:169], v[142:143], off
	global_store_dwordx2 v[238:239], v[138:139], off offset:32
	s_waitcnt lgkmcnt(0)
	v_add_f32_e32 v0, v0, v130
	ds_bpermute_b32 v130, v175, v0
	s_waitcnt lgkmcnt(0)
	v_add_f32_e32 v0, v0, v130
	v_fmamk_f32 v0, v0, 0x3c800000, v187
	v_cmp_gt_f32_e32 vcc, s3, v0
	v_mul_f32_e32 v130, 0x4f800000, v0
	s_nop 0
	v_cndmask_b32_e32 v0, v0, v130, vcc
	v_sqrt_f32_e32 v130, v0
	s_nop 0
	v_add_u32_e32 v131, -1, v130
	v_fma_f32 v132, -v131, v130, v0
	v_cmp_ge_f32_e64 s[0:1], 0, v132
	v_add_u32_e32 v132, 1, v130
	s_nop 0
	v_cndmask_b32_e64 v131, v130, v131, s[0:1]
	v_fma_f32 v130, -v132, v130, v0
	v_cmp_lt_f32_e64 s[0:1], 0, v130
	s_nop 1
	v_cndmask_b32_e64 v130, v131, v132, s[0:1]
	v_mul_f32_e32 v131, 0x37800000, v130
	v_cndmask_b32_e32 v130, v130, v131, vcc
	v_cmp_class_f32_e32 vcc, v0, v202
	s_nop 1
	v_cndmask_b32_e32 v0, v130, v0, vcc
	v_div_scale_f32 v130, s[0:1], v0, v0, 1.0
	v_rcp_f32_e32 v131, v130
	s_nop 0
	v_fma_f32 v132, -v130, v131, 1.0
	v_fmac_f32_e32 v131, v132, v131
	v_div_scale_f32 v132, vcc, 1.0, v0, 1.0
	v_mul_f32_e32 v133, v132, v131
	v_fma_f32 v134, -v130, v133, v132
	v_fmac_f32_e32 v133, v134, v131
	v_fma_f32 v130, -v130, v133, v132
	v_div_fmas_f32 v130, v130, v131, v133
	v_div_fixup_f32 v0, v130, v0, 1.0
	v_pk_mul_f32 v[126:127], v[126:127], v[0:1] op_sel_hi:[1,0]
	v_pk_mul_f32 v[128:129], v[128:129], v[0:1] op_sel_hi:[1,0]
	v_pk_mul_f32 v[122:123], v[122:123], v[0:1] op_sel_hi:[1,0]
	v_pk_mul_f32 v[124:125], v[124:125], v[0:1] op_sel_hi:[1,0]
	v_pk_mul_f32 v[118:119], v[118:119], v[0:1] op_sel_hi:[1,0]
	v_pk_mul_f32 v[120:121], v[120:121], v[0:1] op_sel_hi:[1,0]
	v_pk_mul_f32 v[114:115], v[114:115], v[0:1] op_sel_hi:[1,0]
	v_pk_mul_f32 v[116:117], v[116:117], v[0:1] op_sel_hi:[1,0]
	v_cndmask_b32_e64 v0, 0, 1, s[22:23]
	v_pk_mul_f32 v[128:129], v[80:81], v[128:129]
	v_pk_mul_f32 v[126:127], v[78:79], v[126:127]
	v_pk_mul_f32 v[124:125], v[76:77], v[124:125]
	v_pk_mul_f32 v[122:123], v[74:75], v[122:123]
	v_pk_mul_f32 v[120:121], v[72:73], v[120:121]
	v_pk_mul_f32 v[118:119], v[70:71], v[118:119]
	v_pk_mul_f32 v[116:117], v[68:69], v[116:117]
	v_pk_mul_f32 v[114:115], v[66:67], v[114:115]
	v_add_u32_e32 v130, 16, v164
	v_cmp_ne_u32_e64 s[42:43], 1, v0
	s_andn2_b64 vcc, exec, s[22:23]
	s_cbranch_vccnz .LBB0_884
	v_ashrrev_i32_e32 v132, 8, v130
	v_ashrrev_i32_e32 v133, 31, v132
	v_lshlrev_b64 v[132:133], 19, v[132:133]
	v_lshlrev_b32_e32 v0, 10, v130
	v_lshl_add_u64 v[132:133], s[92:93], 0, v[132:133]
	v_and_b32_e32 v0, 0x3fc00, v0
	v_lshl_add_u64 v[132:133], v[132:133], 0, v[0:1]
	v_lshl_add_u64 v[132:133], s[62:63], 2, v[132:133]
	v_lshl_add_u64 v[132:133], v[158:159], 2, v[132:133]
	global_store_dwordx4 v[132:133], v[126:129], off
	global_store_dwordx4 v[132:133], v[122:125], off offset:64
	global_store_dwordx4 v[132:133], v[118:121], off offset:128
	global_store_dwordx4 v[132:133], v[114:117], off offset:192

.LBB0_886:
	v_cndmask_b32_e64 v0, 0, 1, s[30:31]
	s_mov_b32 s6, 0x3e38aa3b
	v_ashrrev_i32_e32 v131, 31, v130
	v_cmp_ne_u32_e64 s[44:45], 1, v0
	s_andn2_b64 vcc, exec, s[30:31]
	s_mov_b64 s[0:1], -1
	s_cbranch_vccnz .LBB0_888
	v_mov_b64_e32 v[132:133], s[18:19]
	v_lshrrev_b32_e32 v244, 2, v130
	v_and_b32_e32 v245, 3, v130
	v_lshlrev_b32_e32 v244, 11, v244
	v_lshl_or_b32 v244, v245, 4, v244
	v_lshrrev_b32_e32 v245, 3, v158
	v_mul_u32_u24_e32 v245, 48, v245
	v_add_u32_e32 v244, v244, v245
	v_mov_b32_e32 v245, 0
	v_lshl_add_u64 v[132:133], v[132:133], 0, v[244:245]
	v_lshl_add_u64 v[132:133], s[62:63], 3, v[132:133]
	s_mov_b64 s[100:101], 0x60
	s_mov_b64 s[0:1], 0
.LBB0_888:
	s_andn2_b64 vcc, exec, s[0:1]
	s_cbranch_vccnz .LBB0_890
	v_lshlrev_b64 v[130:131], 11, v[130:131]
	v_lshl_add_u64 v[130:131], s[16:17], 0, v[130:131]
	v_lshl_add_u64 v[132:133], s[64:65], 1, v[130:131]
	s_mov_b64 s[100:101], 0
	v_pk_mul_f32 v[128:129], v[128:129], s[6:7] op_sel_hi:[1,0]
	v_pk_mul_f32 v[126:127], v[126:127], s[6:7] op_sel_hi:[1,0]
	v_pk_mul_f32 v[124:125], v[124:125], s[6:7] op_sel_hi:[1,0]
	v_pk_mul_f32 v[122:123], v[122:123], s[6:7] op_sel_hi:[1,0]
	v_pk_mul_f32 v[120:121], v[120:121], s[6:7] op_sel_hi:[1,0]
	v_pk_mul_f32 v[118:119], v[118:119], s[6:7] op_sel_hi:[1,0]
	v_pk_mul_f32 v[116:117], v[116:117], s[6:7] op_sel_hi:[1,0]
	v_pk_mul_f32 v[114:115], v[114:115], s[6:7] op_sel_hi:[1,0]
.LBB0_890:
	v_lshl_add_u64 v[130:131], v[158:159], 1, v[132:133]
	v_lshl_add_u64 v[238:239], v[130:131], 0, s[100:101]
	v_lshl_add_u64 v[240:241], v[238:239], 0, s[100:101]
	v_lshl_add_u64 v[242:243], v[240:241], 0, s[100:101]
	v_cvt_pk_bf16_f32 v114, v114, v115
	v_cvt_pk_bf16_f32 v115, v116, v117
	v_cvt_pk_bf16_f32 v118, v118, v119
	v_cvt_pk_bf16_f32 v119, v120, v121
	global_store_dwordx2 v[242:243], v[114:115], off offset:96
	v_pk_mul_f32 v[114:115], v[112:113], v[112:113]
	v_pk_mul_f32 v[116:117], v[110:111], v[110:111]
	global_store_dwordx2 v[240:241], v[118:119], off offset:64
	v_pk_mov_b32 v[118:119], v[116:117], v[114:115] op_sel:[1,0]
	v_mov_b32_e32 v117, v115
	v_pk_add_f32 v[114:115], v[118:119], v[116:117]
	v_pk_mul_f32 v[116:117], v[108:109], v[108:109]
	v_pk_mul_f32 v[118:119], v[106:107], v[106:107]
	v_mul_f32_e32 v0, v98, v98
	v_pk_mov_b32 v[120:121], v[118:119], v[116:117] op_sel:[1,0]
	v_mov_b32_e32 v119, v117
	v_pk_add_f32 v[116:117], v[120:121], v[118:119]
	v_mul_f32_e32 v118, v99, v99
	v_pk_add_f32 v[114:115], v[114:115], v[114:115] op_sel:[0,1] op_sel_hi:[1,0]
	v_pk_add_f32 v[116:117], v[116:117], v[116:117] op_sel:[0,1] op_sel_hi:[1,0]
	v_mov_b32_e32 v115, v0
	v_mov_b32_e32 v117, v118
	v_mul_f32_e32 v0, v103, v103
	v_mul_f32_e32 v119, v100, v100
	v_pk_add_f32 v[114:115], v[114:115], v[116:117]
	v_pk_fma_f32 v[116:117], v[102:103], v[102:103], v[0:1] op_sel_hi:[1,1,0]
	v_mul_f32_e32 v0, v105, v105
	v_mul_f32_e32 v120, v101, v101
	v_mov_b32_e32 v117, v119
	v_pk_fma_f32 v[118:119], v[104:105], v[104:105], v[0:1] op_sel_hi:[1,1,0]
	v_cvt_pk_bf16_f32 v126, v126, v127
	v_mov_b32_e32 v119, v120
	v_pk_add_f32 v[116:117], v[116:117], v[118:119]
	v_cvt_pk_bf16_f32 v127, v128, v129
	v_pk_add_f32 v[114:115], v[114:115], v[116:117]
	v_cvt_pk_bf16_f32 v122, v122, v123
	v_add_f32_e32 v0, v114, v115
	ds_bpermute_b32 v114, v174, v0
	v_cvt_pk_bf16_f32 v123, v124, v125
	global_store_dwordx2 v[130:131], v[126:127], off
	global_store_dwordx2 v[238:239], v[122:123], off offset:32
	s_waitcnt lgkmcnt(0)
	v_add_f32_e32 v0, v0, v114
	ds_bpermute_b32 v114, v175, v0
	s_waitcnt lgkmcnt(0)
	v_add_f32_e32 v0, v0, v114
	v_fmamk_f32 v0, v0, 0x3c800000, v187
	v_cmp_gt_f32_e32 vcc, s3, v0
	v_mul_f32_e32 v114, 0x4f800000, v0
	s_nop 0
	v_cndmask_b32_e32 v0, v0, v114, vcc
	v_sqrt_f32_e32 v114, v0
	s_nop 0
	v_add_u32_e32 v115, -1, v114
	v_fma_f32 v116, -v115, v114, v0
	v_cmp_ge_f32_e64 s[0:1], 0, v116
	v_add_u32_e32 v116, 1, v114
	s_nop 0
	v_cndmask_b32_e64 v115, v114, v115, s[0:1]
	v_fma_f32 v114, -v116, v114, v0
	v_cmp_lt_f32_e64 s[0:1], 0, v114
	s_nop 1
	v_cndmask_b32_e64 v114, v115, v116, s[0:1]
	v_mul_f32_e32 v115, 0x37800000, v114
	v_cndmask_b32_e32 v114, v114, v115, vcc
	v_cmp_class_f32_e32 vcc, v0, v202
	s_nop 1
	v_cndmask_b32_e32 v0, v114, v0, vcc
	v_div_scale_f32 v114, s[0:1], v0, v0, 1.0
	v_rcp_f32_e32 v115, v114
	s_nop 0
	v_fma_f32 v116, -v114, v115, 1.0
	v_fmac_f32_e32 v115, v116, v115
	v_div_scale_f32 v116, vcc, 1.0, v0, 1.0
	v_mul_f32_e32 v117, v116, v115
	v_fma_f32 v118, -v114, v117, v116
	v_fmac_f32_e32 v117, v118, v115
	v_fma_f32 v114, -v114, v117, v116
	v_div_fmas_f32 v114, v114, v115, v117
	v_div_fixup_f32 v0, v114, v0, 1.0
	v_pk_mul_f32 v[110:111], v[110:111], v[0:1] op_sel_hi:[1,0]
	v_pk_mul_f32 v[112:113], v[112:113], v[0:1] op_sel_hi:[1,0]
	v_pk_mul_f32 v[106:107], v[106:107], v[0:1] op_sel_hi:[1,0]
	v_pk_mul_f32 v[108:109], v[108:109], v[0:1] op_sel_hi:[1,0]
	v_pk_mul_f32 v[102:103], v[102:103], v[0:1] op_sel_hi:[1,0]
	v_pk_mul_f32 v[104:105], v[104:105], v[0:1] op_sel_hi:[1,0]
	v_pk_mul_f32 v[98:99], v[98:99], v[0:1] op_sel_hi:[1,0]
	v_pk_mul_f32 v[100:101], v[100:101], v[0:1] op_sel_hi:[1,0]
	v_pk_mul_f32 v[112:113], v[80:81], v[112:113]
	v_pk_mul_f32 v[110:111], v[78:79], v[110:111]
	v_pk_mul_f32 v[108:109], v[76:77], v[108:109]
	v_pk_mul_f32 v[106:107], v[74:75], v[106:107]
	v_pk_mul_f32 v[104:105], v[72:73], v[104:105]
	v_pk_mul_f32 v[102:103], v[70:71], v[102:103]
	v_pk_mul_f32 v[100:101], v[68:69], v[100:101]
	v_pk_mul_f32 v[98:99], v[66:67], v[98:99]
	v_add_u32_e32 v114, 32, v164
	s_and_b64 vcc, exec, s[42:43]
	s_cbranch_vccnz .LBB0_892
	v_ashrrev_i32_e32 v116, 8, v114
	v_ashrrev_i32_e32 v117, 31, v116
	v_lshlrev_b64 v[116:117], 19, v[116:117]
	v_lshlrev_b32_e32 v0, 10, v114
	v_lshl_add_u64 v[116:117], s[92:93], 0, v[116:117]
	v_and_b32_e32 v0, 0x3fc00, v0
	v_lshl_add_u64 v[116:117], v[116:117], 0, v[0:1]
	v_lshl_add_u64 v[116:117], s[62:63], 2, v[116:117]
	v_lshl_add_u64 v[116:117], v[158:159], 2, v[116:117]
	global_store_dwordx4 v[116:117], v[110:113], off
	global_store_dwordx4 v[116:117], v[106:109], off offset:64
	global_store_dwordx4 v[116:117], v[102:105], off offset:128
	global_store_dwordx4 v[116:117], v[98:101], off offset:192
	s_and_b64 vcc, exec, s[40:41]
	s_cbranch_vccnz .LBB0_894
	s_branch .LBB0_893

.LBB0_894:
	v_ashrrev_i32_e32 v115, 31, v114
	s_and_b64 vcc, exec, s[44:45]
	s_mov_b64 s[0:1], -1
	s_cbranch_vccnz .LBB0_896
	v_mov_b64_e32 v[116:117], s[18:19]
	v_lshrrev_b32_e32 v244, 2, v114
	v_and_b32_e32 v245, 3, v114
	v_lshlrev_b32_e32 v244, 11, v244
	v_lshl_or_b32 v244, v245, 4, v244
	v_lshrrev_b32_e32 v245, 3, v158
	v_mul_u32_u24_e32 v245, 48, v245
	v_add_u32_e32 v244, v244, v245
	v_mov_b32_e32 v245, 0
	v_lshl_add_u64 v[116:117], v[116:117], 0, v[244:245]
	v_lshl_add_u64 v[116:117], s[62:63], 3, v[116:117]
	s_mov_b64 s[100:101], 0x60
	s_cbranch_execz .LBB0_897
	s_branch .LBB0_898

.LBB0_897:
	v_lshlrev_b64 v[114:115], 11, v[114:115]
	v_lshl_add_u64 v[114:115], s[16:17], 0, v[114:115]
	v_lshl_add_u64 v[116:117], s[64:65], 1, v[114:115]
	s_mov_b64 s[100:101], 0
	v_pk_mul_f32 v[112:113], v[112:113], s[6:7] op_sel_hi:[1,0]
	v_pk_mul_f32 v[110:111], v[110:111], s[6:7] op_sel_hi:[1,0]
	v_pk_mul_f32 v[108:109], v[108:109], s[6:7] op_sel_hi:[1,0]
	v_pk_mul_f32 v[106:107], v[106:107], s[6:7] op_sel_hi:[1,0]
	v_pk_mul_f32 v[104:105], v[104:105], s[6:7] op_sel_hi:[1,0]
	v_pk_mul_f32 v[102:103], v[102:103], s[6:7] op_sel_hi:[1,0]
	v_pk_mul_f32 v[100:101], v[100:101], s[6:7] op_sel_hi:[1,0]
	v_pk_mul_f32 v[98:99], v[98:99], s[6:7] op_sel_hi:[1,0]
.LBB0_898:
	v_lshl_add_u64 v[114:115], v[158:159], 1, v[116:117]
	v_lshl_add_u64 v[238:239], v[114:115], 0, s[100:101]
	v_lshl_add_u64 v[240:241], v[238:239], 0, s[100:101]
	v_lshl_add_u64 v[242:243], v[240:241], 0, s[100:101]
	v_cvt_pk_bf16_f32 v98, v98, v99
	v_cvt_pk_bf16_f32 v99, v100, v101
	v_cvt_pk_bf16_f32 v102, v102, v103
	v_cvt_pk_bf16_f32 v103, v104, v105
	global_store_dwordx2 v[242:243], v[98:99], off offset:96
	v_pk_mul_f32 v[98:99], v[96:97], v[96:97]
	v_pk_mul_f32 v[100:101], v[94:95], v[94:95]
	global_store_dwordx2 v[240:241], v[102:103], off offset:64
	v_pk_mov_b32 v[102:103], v[100:101], v[98:99] op_sel:[1,0]
	v_mov_b32_e32 v101, v99
	v_pk_add_f32 v[98:99], v[102:103], v[100:101]
	v_pk_mul_f32 v[100:101], v[92:93], v[92:93]
	v_pk_mul_f32 v[102:103], v[90:91], v[90:91]
	v_mul_f32_e32 v0, v82, v82
	v_pk_mov_b32 v[104:105], v[102:103], v[100:101] op_sel:[1,0]
	v_mov_b32_e32 v103, v101
	v_pk_add_f32 v[100:101], v[104:105], v[102:103]
	v_mul_f32_e32 v102, v83, v83
	v_pk_add_f32 v[98:99], v[98:99], v[98:99] op_sel:[0,1] op_sel_hi:[1,0]
	v_pk_add_f32 v[100:101], v[100:101], v[100:101] op_sel:[0,1] op_sel_hi:[1,0]
	v_mov_b32_e32 v99, v0
	v_mov_b32_e32 v101, v102
	v_mul_f32_e32 v0, v87, v87
	v_mul_f32_e32 v103, v84, v84
	v_pk_add_f32 v[98:99], v[98:99], v[100:101]
	v_pk_fma_f32 v[100:101], v[86:87], v[86:87], v[0:1] op_sel_hi:[1,1,0]
	v_mul_f32_e32 v0, v89, v89
	v_mul_f32_e32 v104, v85, v85
	v_mov_b32_e32 v101, v103
	v_pk_fma_f32 v[102:103], v[88:89], v[88:89], v[0:1] op_sel_hi:[1,1,0]
	v_cvt_pk_bf16_f32 v110, v110, v111
	v_mov_b32_e32 v103, v104
	v_pk_add_f32 v[100:101], v[100:101], v[102:103]
	v_cvt_pk_bf16_f32 v111, v112, v113
	v_pk_add_f32 v[98:99], v[98:99], v[100:101]
	v_cvt_pk_bf16_f32 v106, v106, v107
	v_add_f32_e32 v0, v98, v99
	ds_bpermute_b32 v98, v174, v0
	v_cvt_pk_bf16_f32 v107, v108, v109
	global_store_dwordx2 v[114:115], v[110:111], off
	global_store_dwordx2 v[238:239], v[106:107], off offset:32
	s_waitcnt lgkmcnt(0)
	v_add_f32_e32 v0, v0, v98
	ds_bpermute_b32 v98, v175, v0
	s_waitcnt lgkmcnt(0)
	v_add_f32_e32 v0, v0, v98
	v_fmamk_f32 v0, v0, 0x3c800000, v187
	v_cmp_gt_f32_e32 vcc, s3, v0
	v_mul_f32_e32 v98, 0x4f800000, v0
	s_nop 0
	v_cndmask_b32_e32 v0, v0, v98, vcc
	v_sqrt_f32_e32 v98, v0
	s_nop 0
	v_add_u32_e32 v99, -1, v98
	v_fma_f32 v100, -v99, v98, v0
	v_cmp_ge_f32_e64 s[0:1], 0, v100
	v_add_u32_e32 v100, 1, v98
	s_nop 0
	v_cndmask_b32_e64 v99, v98, v99, s[0:1]
	v_fma_f32 v98, -v100, v98, v0
	v_cmp_lt_f32_e64 s[0:1], 0, v98
	s_nop 1
	v_cndmask_b32_e64 v98, v99, v100, s[0:1]
	v_mul_f32_e32 v99, 0x37800000, v98
	v_cndmask_b32_e32 v98, v98, v99, vcc
	v_cmp_class_f32_e32 vcc, v0, v202
	s_nop 1
	v_cndmask_b32_e32 v0, v98, v0, vcc
	v_div_scale_f32 v98, s[0:1], v0, v0, 1.0
	v_rcp_f32_e32 v99, v98
	s_nop 0
	v_fma_f32 v100, -v98, v99, 1.0
	v_fmac_f32_e32 v99, v100, v99
	v_div_scale_f32 v100, vcc, 1.0, v0, 1.0
	v_mul_f32_e32 v101, v100, v99
	v_fma_f32 v102, -v98, v101, v100
	v_fmac_f32_e32 v101, v102, v99
	v_fma_f32 v98, -v98, v101, v100
	v_div_fmas_f32 v98, v98, v99, v101
	v_div_fixup_f32 v0, v98, v0, 1.0
	v_pk_mul_f32 v[94:95], v[94:95], v[0:1] op_sel_hi:[1,0]
	v_pk_mul_f32 v[96:97], v[96:97], v[0:1] op_sel_hi:[1,0]
	v_pk_mul_f32 v[90:91], v[90:91], v[0:1] op_sel_hi:[1,0]
	v_pk_mul_f32 v[92:93], v[92:93], v[0:1] op_sel_hi:[1,0]
	v_pk_mul_f32 v[86:87], v[86:87], v[0:1] op_sel_hi:[1,0]
	v_pk_mul_f32 v[88:89], v[88:89], v[0:1] op_sel_hi:[1,0]
	v_pk_mul_f32 v[82:83], v[82:83], v[0:1] op_sel_hi:[1,0]
	v_pk_mul_f32 v[84:85], v[84:85], v[0:1] op_sel_hi:[1,0]
	v_pk_mul_f32 v[96:97], v[80:81], v[96:97]
	v_pk_mul_f32 v[94:95], v[78:79], v[94:95]
	v_pk_mul_f32 v[92:93], v[76:77], v[92:93]
	v_pk_mul_f32 v[90:91], v[74:75], v[90:91]
	v_pk_mul_f32 v[88:89], v[72:73], v[88:89]
	v_pk_mul_f32 v[86:87], v[70:71], v[86:87]
	v_pk_mul_f32 v[84:85], v[68:69], v[84:85]
	v_pk_mul_f32 v[82:83], v[66:67], v[82:83]
	v_add_u32_e32 v98, 48, v164
	s_and_b64 vcc, exec, s[42:43]
	s_cbranch_vccnz .LBB0_900
	v_ashrrev_i32_e32 v100, 8, v98
	v_ashrrev_i32_e32 v101, 31, v100
	v_lshlrev_b64 v[100:101], 19, v[100:101]
	v_lshlrev_b32_e32 v0, 10, v98
	v_lshl_add_u64 v[100:101], s[92:93], 0, v[100:101]
	v_and_b32_e32 v0, 0x3fc00, v0
	v_lshl_add_u64 v[100:101], v[100:101], 0, v[0:1]
	v_lshl_add_u64 v[100:101], s[62:63], 2, v[100:101]
	v_lshl_add_u64 v[100:101], v[158:159], 2, v[100:101]
	global_store_dwordx4 v[100:101], v[94:97], off
	global_store_dwordx4 v[100:101], v[90:93], off offset:64
	global_store_dwordx4 v[100:101], v[86:89], off offset:128
	global_store_dwordx4 v[100:101], v[82:85], off offset:192
	s_and_b64 vcc, exec, s[40:41]
	s_cbranch_vccnz .LBB0_902
	s_branch .LBB0_901

.LBB0_902:
	v_ashrrev_i32_e32 v99, 31, v98
	s_and_b64 vcc, exec, s[44:45]
	s_mov_b64 s[0:1], -1
	s_cbranch_vccnz .LBB0_904
	v_mov_b64_e32 v[100:101], s[18:19]
	v_lshrrev_b32_e32 v244, 2, v98
	v_and_b32_e32 v245, 3, v98
	v_lshlrev_b32_e32 v244, 11, v244
	v_lshl_or_b32 v244, v245, 4, v244
	v_lshrrev_b32_e32 v245, 3, v158
	v_mul_u32_u24_e32 v245, 48, v245
	v_add_u32_e32 v244, v244, v245
	v_mov_b32_e32 v245, 0
	v_lshl_add_u64 v[100:101], v[100:101], 0, v[244:245]
	v_lshl_add_u64 v[100:101], s[62:63], 3, v[100:101]
	s_mov_b64 s[100:101], 0x60
	s_cbranch_execz .LBB0_905
	s_branch .LBB0_906

.LBB0_905:
	v_lshlrev_b64 v[98:99], 11, v[98:99]
	v_lshl_add_u64 v[98:99], s[16:17], 0, v[98:99]
	v_lshl_add_u64 v[100:101], s[64:65], 1, v[98:99]
	s_mov_b64 s[100:101], 0
	v_pk_mul_f32 v[96:97], v[96:97], s[6:7] op_sel_hi:[1,0]
	v_pk_mul_f32 v[94:95], v[94:95], s[6:7] op_sel_hi:[1,0]
	v_pk_mul_f32 v[92:93], v[92:93], s[6:7] op_sel_hi:[1,0]
	v_pk_mul_f32 v[90:91], v[90:91], s[6:7] op_sel_hi:[1,0]
	v_pk_mul_f32 v[88:89], v[88:89], s[6:7] op_sel_hi:[1,0]
	v_pk_mul_f32 v[86:87], v[86:87], s[6:7] op_sel_hi:[1,0]
	v_pk_mul_f32 v[84:85], v[84:85], s[6:7] op_sel_hi:[1,0]
	v_pk_mul_f32 v[82:83], v[82:83], s[6:7] op_sel_hi:[1,0]
.LBB0_906:
	v_lshl_add_u64 v[98:99], v[158:159], 1, v[100:101]
	v_lshl_add_u64 v[238:239], v[98:99], 0, s[100:101]
	v_lshl_add_u64 v[240:241], v[238:239], 0, s[100:101]
	v_lshl_add_u64 v[242:243], v[240:241], 0, s[100:101]
	v_cvt_pk_bf16_f32 v86, v86, v87
	v_cvt_pk_bf16_f32 v87, v88, v89
	global_store_dwordx2 v[240:241], v[86:87], off offset:64
	v_cvt_pk_bf16_f32 v82, v82, v83
	v_cvt_pk_bf16_f32 v83, v84, v85
	v_pk_mul_f32 v[84:85], v[64:65], v[64:65]
	v_pk_mul_f32 v[86:87], v[62:63], v[62:63]
	v_cvt_pk_bf16_f32 v90, v90, v91
	v_pk_mov_b32 v[88:89], v[86:87], v[84:85] op_sel:[1,0]
	v_mov_b32_e32 v87, v85
	v_cvt_pk_bf16_f32 v91, v92, v93
	v_pk_add_f32 v[84:85], v[88:89], v[86:87]
	v_pk_mul_f32 v[86:87], v[60:61], v[60:61]
	v_pk_mul_f32 v[88:89], v[58:59], v[58:59]
	global_store_dwordx2 v[238:239], v[90:91], off offset:32
	v_pk_mov_b32 v[90:91], v[88:89], v[86:87] op_sel:[1,0]
	v_mov_b32_e32 v89, v87
	v_pk_add_f32 v[86:87], v[90:91], v[88:89]
	global_store_dwordx2 v[242:243], v[82:83], off offset:96
	v_mul_f32_e32 v0, v50, v50
	v_mul_f32_e32 v83, v51, v51
	v_pk_add_f32 v[84:85], v[84:85], v[84:85] op_sel:[0,1] op_sel_hi:[1,0]
	v_pk_add_f32 v[86:87], v[86:87], v[86:87] op_sel:[0,1] op_sel_hi:[1,0]
	v_mov_b32_e32 v85, v0
	v_mov_b32_e32 v87, v83
	v_mul_f32_e32 v0, v55, v55
	v_mul_f32_e32 v88, v52, v52
	v_pk_add_f32 v[84:85], v[84:85], v[86:87]
	v_pk_fma_f32 v[86:87], v[54:55], v[54:55], v[0:1] op_sel_hi:[1,1,0]
	v_mul_f32_e32 v0, v57, v57
	v_mul_f32_e32 v90, v53, v53
	v_mov_b32_e32 v87, v88
	v_pk_fma_f32 v[88:89], v[56:57], v[56:57], v[0:1] op_sel_hi:[1,1,0]
	v_cvt_pk_bf16_f32 v94, v94, v95
	v_mov_b32_e32 v89, v90
	v_pk_add_f32 v[86:87], v[86:87], v[88:89]
	v_cvt_pk_bf16_f32 v95, v96, v97
	v_pk_add_f32 v[84:85], v[84:85], v[86:87]
	v_add_u32_e32 v82, 0x80, v164
	v_add_f32_e32 v0, v84, v85
	ds_bpermute_b32 v83, v174, v0
	global_store_dwordx2 v[98:99], v[94:95], off
	s_waitcnt lgkmcnt(0)
	v_add_f32_e32 v0, v0, v83
	ds_bpermute_b32 v83, v175, v0
	s_waitcnt lgkmcnt(0)
	v_add_f32_e32 v0, v0, v83
	v_fmamk_f32 v0, v0, 0x3c800000, v187
	v_cmp_gt_f32_e32 vcc, s3, v0
	v_mul_f32_e32 v83, 0x4f800000, v0
	s_nop 0
	v_cndmask_b32_e32 v0, v0, v83, vcc
	v_sqrt_f32_e32 v83, v0
	s_nop 0
	v_add_u32_e32 v84, -1, v83
	v_fma_f32 v85, -v84, v83, v0
	v_cmp_ge_f32_e64 s[0:1], 0, v85
	v_add_u32_e32 v85, 1, v83
	s_nop 0
	v_cndmask_b32_e64 v84, v83, v84, s[0:1]
	v_fma_f32 v83, -v85, v83, v0
	v_cmp_lt_f32_e64 s[0:1], 0, v83
	s_nop 1
	v_cndmask_b32_e64 v83, v84, v85, s[0:1]
	v_mul_f32_e32 v84, 0x37800000, v83
	v_cndmask_b32_e32 v83, v83, v84, vcc
	v_cmp_class_f32_e32 vcc, v0, v202
	s_nop 1
	v_cndmask_b32_e32 v0, v83, v0, vcc
	v_div_scale_f32 v83, s[0:1], v0, v0, 1.0
	v_rcp_f32_e32 v84, v83
	s_nop 0
	v_fma_f32 v85, -v83, v84, 1.0
	v_fmac_f32_e32 v84, v85, v84
	v_div_scale_f32 v85, vcc, 1.0, v0, 1.0
	v_mul_f32_e32 v86, v85, v84
	v_fma_f32 v87, -v83, v86, v85
	v_fmac_f32_e32 v86, v87, v84
	v_fma_f32 v83, -v83, v86, v85
	v_div_fmas_f32 v83, v83, v84, v86
	v_div_fixup_f32 v0, v83, v0, 1.0
	v_pk_mul_f32 v[62:63], v[62:63], v[0:1] op_sel_hi:[1,0]
	v_pk_mul_f32 v[64:65], v[64:65], v[0:1] op_sel_hi:[1,0]
	v_pk_mul_f32 v[58:59], v[58:59], v[0:1] op_sel_hi:[1,0]
	v_pk_mul_f32 v[60:61], v[60:61], v[0:1] op_sel_hi:[1,0]
	v_pk_mul_f32 v[54:55], v[54:55], v[0:1] op_sel_hi:[1,0]
	v_pk_mul_f32 v[56:57], v[56:57], v[0:1] op_sel_hi:[1,0]
	v_pk_mul_f32 v[50:51], v[50:51], v[0:1] op_sel_hi:[1,0]
	v_pk_mul_f32 v[52:53], v[52:53], v[0:1] op_sel_hi:[1,0]
	v_pk_mul_f32 v[64:65], v[80:81], v[64:65]
	v_pk_mul_f32 v[62:63], v[78:79], v[62:63]
	v_pk_mul_f32 v[60:61], v[76:77], v[60:61]
	v_pk_mul_f32 v[58:59], v[74:75], v[58:59]
	v_pk_mul_f32 v[56:57], v[72:73], v[56:57]
	v_pk_mul_f32 v[54:55], v[70:71], v[54:55]
	v_pk_mul_f32 v[52:53], v[68:69], v[52:53]
	v_pk_mul_f32 v[50:51], v[66:67], v[50:51]
	s_and_b64 vcc, exec, s[42:43]
	s_cbranch_vccnz .LBB0_908
	v_ashrrev_i32_e32 v84, 8, v82
	v_ashrrev_i32_e32 v85, 31, v84
	v_lshlrev_b64 v[84:85], 19, v[84:85]
	v_lshlrev_b32_e32 v0, 10, v82
	v_lshl_add_u64 v[84:85], s[92:93], 0, v[84:85]
	v_and_b32_e32 v0, 0x3fc00, v0
	v_lshl_add_u64 v[84:85], v[84:85], 0, v[0:1]
	v_lshl_add_u64 v[84:85], s[62:63], 2, v[84:85]
	v_lshl_add_u64 v[84:85], v[158:159], 2, v[84:85]
	global_store_dwordx4 v[84:85], v[62:65], off
	global_store_dwordx4 v[84:85], v[58:61], off offset:64
	global_store_dwordx4 v[84:85], v[54:57], off offset:128
	global_store_dwordx4 v[84:85], v[50:53], off offset:192
	s_and_b64 vcc, exec, s[40:41]
	s_cbranch_vccnz .LBB0_910
	s_branch .LBB0_909

.LBB0_910:
	v_ashrrev_i32_e32 v83, 31, v82
	s_and_b64 vcc, exec, s[44:45]
	s_mov_b64 s[0:1], -1
	s_cbranch_vccnz .LBB0_912
	v_mov_b64_e32 v[84:85], s[18:19]
	v_lshrrev_b32_e32 v244, 2, v82
	v_and_b32_e32 v245, 3, v82
	v_lshlrev_b32_e32 v244, 11, v244
	v_lshl_or_b32 v244, v245, 4, v244
	v_lshrrev_b32_e32 v245, 3, v158
	v_mul_u32_u24_e32 v245, 48, v245
	v_add_u32_e32 v244, v244, v245
	v_mov_b32_e32 v245, 0
	v_lshl_add_u64 v[84:85], v[84:85], 0, v[244:245]
	v_lshl_add_u64 v[84:85], s[62:63], 3, v[84:85]
	s_mov_b64 s[100:101], 0x60
	s_cbranch_execz .LBB0_913
	s_branch .LBB0_914

.LBB0_913:
	v_lshlrev_b64 v[82:83], 11, v[82:83]
	v_lshl_add_u64 v[82:83], s[16:17], 0, v[82:83]
	v_lshl_add_u64 v[84:85], s[64:65], 1, v[82:83]
	s_mov_b64 s[100:101], 0
	v_pk_mul_f32 v[64:65], v[64:65], s[6:7] op_sel_hi:[1,0]
	v_pk_mul_f32 v[62:63], v[62:63], s[6:7] op_sel_hi:[1,0]
	v_pk_mul_f32 v[60:61], v[60:61], s[6:7] op_sel_hi:[1,0]
	v_pk_mul_f32 v[58:59], v[58:59], s[6:7] op_sel_hi:[1,0]
	v_pk_mul_f32 v[56:57], v[56:57], s[6:7] op_sel_hi:[1,0]
	v_pk_mul_f32 v[54:55], v[54:55], s[6:7] op_sel_hi:[1,0]
	v_pk_mul_f32 v[52:53], v[52:53], s[6:7] op_sel_hi:[1,0]
	v_pk_mul_f32 v[50:51], v[50:51], s[6:7] op_sel_hi:[1,0]
.LBB0_914:
	v_lshl_add_u64 v[82:83], v[158:159], 1, v[84:85]
	v_lshl_add_u64 v[238:239], v[82:83], 0, s[100:101]
	v_lshl_add_u64 v[240:241], v[238:239], 0, s[100:101]
	v_lshl_add_u64 v[242:243], v[240:241], 0, s[100:101]
	v_cvt_pk_bf16_f32 v50, v50, v51
	v_cvt_pk_bf16_f32 v51, v52, v53
	v_cvt_pk_bf16_f32 v54, v54, v55
	v_cvt_pk_bf16_f32 v55, v56, v57
	global_store_dwordx2 v[242:243], v[50:51], off offset:96
	v_pk_mul_f32 v[50:51], v[48:49], v[48:49]
	v_pk_mul_f32 v[52:53], v[46:47], v[46:47]
	global_store_dwordx2 v[240:241], v[54:55], off offset:64
	v_pk_mov_b32 v[54:55], v[52:53], v[50:51] op_sel:[1,0]
	v_mov_b32_e32 v53, v51
	v_pk_add_f32 v[50:51], v[54:55], v[52:53]
	v_pk_mul_f32 v[52:53], v[44:45], v[44:45]
	v_pk_mul_f32 v[54:55], v[42:43], v[42:43]
	v_mul_f32_e32 v0, v34, v34
	v_pk_mov_b32 v[56:57], v[54:55], v[52:53] op_sel:[1,0]
	v_mov_b32_e32 v55, v53
	v_pk_add_f32 v[52:53], v[56:57], v[54:55]
	v_mul_f32_e32 v54, v35, v35
	v_pk_add_f32 v[50:51], v[50:51], v[50:51] op_sel:[0,1] op_sel_hi:[1,0]
	v_pk_add_f32 v[52:53], v[52:53], v[52:53] op_sel:[0,1] op_sel_hi:[1,0]
	v_mov_b32_e32 v51, v0
	v_mov_b32_e32 v53, v54
	v_mul_f32_e32 v0, v39, v39
	v_mul_f32_e32 v55, v36, v36
	v_pk_add_f32 v[50:51], v[50:51], v[52:53]
	v_pk_fma_f32 v[52:53], v[38:39], v[38:39], v[0:1] op_sel_hi:[1,1,0]
	v_mul_f32_e32 v0, v41, v41
	v_mul_f32_e32 v56, v37, v37
	v_mov_b32_e32 v53, v55
	v_pk_fma_f32 v[54:55], v[40:41], v[40:41], v[0:1] op_sel_hi:[1,1,0]
	v_cvt_pk_bf16_f32 v62, v62, v63
	v_mov_b32_e32 v55, v56
	v_pk_add_f32 v[52:53], v[52:53], v[54:55]
	v_cvt_pk_bf16_f32 v63, v64, v65
	v_pk_add_f32 v[50:51], v[50:51], v[52:53]
	v_cvt_pk_bf16_f32 v58, v58, v59
	v_add_f32_e32 v0, v50, v51
	ds_bpermute_b32 v50, v174, v0
	v_cvt_pk_bf16_f32 v59, v60, v61
	global_store_dwordx2 v[82:83], v[62:63], off
	global_store_dwordx2 v[238:239], v[58:59], off offset:32
	s_waitcnt lgkmcnt(0)
	v_add_f32_e32 v0, v0, v50
	ds_bpermute_b32 v50, v175, v0
	s_waitcnt lgkmcnt(0)
	v_add_f32_e32 v0, v0, v50
	v_fmamk_f32 v0, v0, 0x3c800000, v187
	v_cmp_gt_f32_e32 vcc, s3, v0
	v_mul_f32_e32 v50, 0x4f800000, v0
	s_nop 0
	v_cndmask_b32_e32 v0, v0, v50, vcc
	v_sqrt_f32_e32 v50, v0
	s_nop 0
	v_add_u32_e32 v51, -1, v50
	v_fma_f32 v52, -v51, v50, v0
	v_cmp_ge_f32_e64 s[0:1], 0, v52
	v_add_u32_e32 v52, 1, v50
	s_nop 0
	v_cndmask_b32_e64 v51, v50, v51, s[0:1]
	v_fma_f32 v50, -v52, v50, v0
	v_cmp_lt_f32_e64 s[0:1], 0, v50
	s_nop 1
	v_cndmask_b32_e64 v50, v51, v52, s[0:1]
	v_mul_f32_e32 v51, 0x37800000, v50
	v_cndmask_b32_e32 v50, v50, v51, vcc
	v_cmp_class_f32_e32 vcc, v0, v202
	s_nop 1
	v_cndmask_b32_e32 v0, v50, v0, vcc
	v_div_scale_f32 v50, s[0:1], v0, v0, 1.0
	v_rcp_f32_e32 v51, v50
	s_nop 0
	v_fma_f32 v52, -v50, v51, 1.0
	v_fmac_f32_e32 v51, v52, v51
	v_div_scale_f32 v52, vcc, 1.0, v0, 1.0
	v_mul_f32_e32 v53, v52, v51
	v_fma_f32 v54, -v50, v53, v52
	v_fmac_f32_e32 v53, v54, v51
	v_fma_f32 v50, -v50, v53, v52
	v_div_fmas_f32 v50, v50, v51, v53
	v_div_fixup_f32 v0, v50, v0, 1.0
	v_pk_mul_f32 v[46:47], v[46:47], v[0:1] op_sel_hi:[1,0]
	v_pk_mul_f32 v[48:49], v[48:49], v[0:1] op_sel_hi:[1,0]
	v_pk_mul_f32 v[42:43], v[42:43], v[0:1] op_sel_hi:[1,0]
	v_pk_mul_f32 v[44:45], v[44:45], v[0:1] op_sel_hi:[1,0]
	v_pk_mul_f32 v[38:39], v[38:39], v[0:1] op_sel_hi:[1,0]
	v_pk_mul_f32 v[40:41], v[40:41], v[0:1] op_sel_hi:[1,0]
	v_pk_mul_f32 v[34:35], v[34:35], v[0:1] op_sel_hi:[1,0]
	v_pk_mul_f32 v[36:37], v[36:37], v[0:1] op_sel_hi:[1,0]
	v_pk_mul_f32 v[48:49], v[80:81], v[48:49]
	v_pk_mul_f32 v[46:47], v[78:79], v[46:47]
	v_pk_mul_f32 v[44:45], v[76:77], v[44:45]
	v_pk_mul_f32 v[42:43], v[74:75], v[42:43]
	v_pk_mul_f32 v[40:41], v[72:73], v[40:41]
	v_pk_mul_f32 v[38:39], v[70:71], v[38:39]
	v_pk_mul_f32 v[36:37], v[68:69], v[36:37]
	v_pk_mul_f32 v[34:35], v[66:67], v[34:35]
	v_add_u32_e32 v50, 0x90, v164
	s_and_b64 vcc, exec, s[42:43]
	s_cbranch_vccnz .LBB0_916
	v_ashrrev_i32_e32 v52, 8, v50
	v_ashrrev_i32_e32 v53, 31, v52
	v_lshlrev_b64 v[52:53], 19, v[52:53]
	v_lshlrev_b32_e32 v0, 10, v50
	v_lshl_add_u64 v[52:53], s[92:93], 0, v[52:53]
	v_and_b32_e32 v0, 0x3fc00, v0
	v_lshl_add_u64 v[52:53], v[52:53], 0, v[0:1]
	v_lshl_add_u64 v[52:53], s[62:63], 2, v[52:53]
	v_lshl_add_u64 v[52:53], v[158:159], 2, v[52:53]
	global_store_dwordx4 v[52:53], v[46:49], off
	global_store_dwordx4 v[52:53], v[42:45], off offset:64
	global_store_dwordx4 v[52:53], v[38:41], off offset:128
	global_store_dwordx4 v[52:53], v[34:37], off offset:192
	s_and_b64 vcc, exec, s[40:41]
	s_cbranch_vccnz .LBB0_918
	s_branch .LBB0_917

.LBB0_918:
	v_ashrrev_i32_e32 v51, 31, v50
	s_and_b64 vcc, exec, s[44:45]
	s_mov_b64 s[0:1], -1
	s_cbranch_vccnz .LBB0_920
	v_mov_b64_e32 v[52:53], s[18:19]
	v_lshrrev_b32_e32 v244, 2, v50
	v_and_b32_e32 v245, 3, v50
	v_lshlrev_b32_e32 v244, 11, v244
	v_lshl_or_b32 v244, v245, 4, v244
	v_lshrrev_b32_e32 v245, 3, v158
	v_mul_u32_u24_e32 v245, 48, v245
	v_add_u32_e32 v244, v244, v245
	v_mov_b32_e32 v245, 0
	v_lshl_add_u64 v[52:53], v[52:53], 0, v[244:245]
	v_lshl_add_u64 v[52:53], s[62:63], 3, v[52:53]
	s_mov_b64 s[100:101], 0x60
	s_cbranch_execz .LBB0_921
	s_branch .LBB0_922

.LBB0_921:
	v_lshlrev_b64 v[50:51], 11, v[50:51]
	v_lshl_add_u64 v[50:51], s[16:17], 0, v[50:51]
	v_lshl_add_u64 v[52:53], s[64:65], 1, v[50:51]
	s_mov_b64 s[100:101], 0
	v_pk_mul_f32 v[48:49], v[48:49], s[6:7] op_sel_hi:[1,0]
	v_pk_mul_f32 v[46:47], v[46:47], s[6:7] op_sel_hi:[1,0]
	v_pk_mul_f32 v[44:45], v[44:45], s[6:7] op_sel_hi:[1,0]
	v_pk_mul_f32 v[42:43], v[42:43], s[6:7] op_sel_hi:[1,0]
	v_pk_mul_f32 v[40:41], v[40:41], s[6:7] op_sel_hi:[1,0]
	v_pk_mul_f32 v[38:39], v[38:39], s[6:7] op_sel_hi:[1,0]
	v_pk_mul_f32 v[36:37], v[36:37], s[6:7] op_sel_hi:[1,0]
	v_pk_mul_f32 v[34:35], v[34:35], s[6:7] op_sel_hi:[1,0]
.LBB0_922:
	v_lshl_add_u64 v[50:51], v[158:159], 1, v[52:53]
	v_lshl_add_u64 v[238:239], v[50:51], 0, s[100:101]
	v_lshl_add_u64 v[240:241], v[238:239], 0, s[100:101]
	v_lshl_add_u64 v[242:243], v[240:241], 0, s[100:101]
	v_cvt_pk_bf16_f32 v34, v34, v35
	v_cvt_pk_bf16_f32 v35, v36, v37
	v_cvt_pk_bf16_f32 v38, v38, v39
	v_cvt_pk_bf16_f32 v39, v40, v41
	global_store_dwordx2 v[242:243], v[34:35], off offset:96
	v_pk_mul_f32 v[34:35], v[32:33], v[32:33]
	v_pk_mul_f32 v[36:37], v[30:31], v[30:31]
	global_store_dwordx2 v[240:241], v[38:39], off offset:64
	v_pk_mov_b32 v[38:39], v[36:37], v[34:35] op_sel:[1,0]
	v_mov_b32_e32 v37, v35
	v_pk_add_f32 v[34:35], v[38:39], v[36:37]
	v_pk_mul_f32 v[36:37], v[28:29], v[28:29]
	v_pk_mul_f32 v[38:39], v[26:27], v[26:27]
	v_mul_f32_e32 v0, v18, v18
	v_pk_mov_b32 v[40:41], v[38:39], v[36:37] op_sel:[1,0]
	v_mov_b32_e32 v39, v37
	v_pk_add_f32 v[36:37], v[40:41], v[38:39]
	v_mul_f32_e32 v38, v19, v19
	v_pk_add_f32 v[34:35], v[34:35], v[34:35] op_sel:[0,1] op_sel_hi:[1,0]
	v_pk_add_f32 v[36:37], v[36:37], v[36:37] op_sel:[0,1] op_sel_hi:[1,0]
	v_mov_b32_e32 v35, v0
	v_mov_b32_e32 v37, v38
	v_mul_f32_e32 v0, v23, v23
	v_mul_f32_e32 v39, v20, v20
	v_pk_add_f32 v[34:35], v[34:35], v[36:37]
	v_pk_fma_f32 v[36:37], v[22:23], v[22:23], v[0:1] op_sel_hi:[1,1,0]
	v_mul_f32_e32 v0, v25, v25
	v_mul_f32_e32 v40, v21, v21
	v_mov_b32_e32 v37, v39
	v_pk_fma_f32 v[38:39], v[24:25], v[24:25], v[0:1] op_sel_hi:[1,1,0]
	v_cvt_pk_bf16_f32 v46, v46, v47
	v_mov_b32_e32 v39, v40
	v_pk_add_f32 v[36:37], v[36:37], v[38:39]
	v_cvt_pk_bf16_f32 v47, v48, v49
	v_pk_add_f32 v[34:35], v[34:35], v[36:37]
	v_cvt_pk_bf16_f32 v42, v42, v43
	v_add_f32_e32 v0, v34, v35
	ds_bpermute_b32 v34, v174, v0
	v_cvt_pk_bf16_f32 v43, v44, v45
	global_store_dwordx2 v[50:51], v[46:47], off
	global_store_dwordx2 v[238:239], v[42:43], off offset:32
	s_waitcnt lgkmcnt(0)
	v_add_f32_e32 v0, v0, v34
	ds_bpermute_b32 v34, v175, v0
	s_waitcnt lgkmcnt(0)
	v_add_f32_e32 v0, v0, v34
	v_fmamk_f32 v0, v0, 0x3c800000, v187
	v_cmp_gt_f32_e32 vcc, s3, v0
	v_mul_f32_e32 v34, 0x4f800000, v0
	s_nop 0
	v_cndmask_b32_e32 v0, v0, v34, vcc
	v_sqrt_f32_e32 v34, v0
	s_nop 0
	v_add_u32_e32 v35, -1, v34
	v_fma_f32 v36, -v35, v34, v0
	v_cmp_ge_f32_e64 s[0:1], 0, v36
	v_add_u32_e32 v36, 1, v34
	s_nop 0
	v_cndmask_b32_e64 v35, v34, v35, s[0:1]
	v_fma_f32 v34, -v36, v34, v0
	v_cmp_lt_f32_e64 s[0:1], 0, v34
	s_nop 1
	v_cndmask_b32_e64 v34, v35, v36, s[0:1]
	v_mul_f32_e32 v35, 0x37800000, v34
	v_cndmask_b32_e32 v34, v34, v35, vcc
	v_cmp_class_f32_e32 vcc, v0, v202
	s_nop 1
	v_cndmask_b32_e32 v0, v34, v0, vcc
	v_div_scale_f32 v34, s[0:1], v0, v0, 1.0
	v_rcp_f32_e32 v35, v34
	s_nop 0
	v_fma_f32 v36, -v34, v35, 1.0
	v_fmac_f32_e32 v35, v36, v35
	v_div_scale_f32 v36, vcc, 1.0, v0, 1.0
	v_mul_f32_e32 v37, v36, v35
	v_fma_f32 v38, -v34, v37, v36
	v_fmac_f32_e32 v37, v38, v35
	v_fma_f32 v34, -v34, v37, v36
	v_div_fmas_f32 v34, v34, v35, v37
	v_div_fixup_f32 v0, v34, v0, 1.0
	v_pk_mul_f32 v[30:31], v[30:31], v[0:1] op_sel_hi:[1,0]
	v_pk_mul_f32 v[32:33], v[32:33], v[0:1] op_sel_hi:[1,0]
	v_pk_mul_f32 v[26:27], v[26:27], v[0:1] op_sel_hi:[1,0]
	v_pk_mul_f32 v[28:29], v[28:29], v[0:1] op_sel_hi:[1,0]
	v_pk_mul_f32 v[22:23], v[22:23], v[0:1] op_sel_hi:[1,0]
	v_pk_mul_f32 v[24:25], v[24:25], v[0:1] op_sel_hi:[1,0]
	v_pk_mul_f32 v[18:19], v[18:19], v[0:1] op_sel_hi:[1,0]
	v_pk_mul_f32 v[20:21], v[20:21], v[0:1] op_sel_hi:[1,0]
	v_pk_mul_f32 v[32:33], v[80:81], v[32:33]
	v_pk_mul_f32 v[30:31], v[78:79], v[30:31]
	v_pk_mul_f32 v[28:29], v[76:77], v[28:29]
	v_pk_mul_f32 v[26:27], v[74:75], v[26:27]
	v_pk_mul_f32 v[24:25], v[72:73], v[24:25]
	v_pk_mul_f32 v[22:23], v[70:71], v[22:23]
	v_pk_mul_f32 v[20:21], v[68:69], v[20:21]
	v_pk_mul_f32 v[18:19], v[66:67], v[18:19]
	v_add_u32_e32 v34, 0xa0, v164
	s_and_b64 vcc, exec, s[42:43]
	s_cbranch_vccnz .LBB0_924
	v_ashrrev_i32_e32 v36, 8, v34
	v_ashrrev_i32_e32 v37, 31, v36
	v_lshlrev_b64 v[36:37], 19, v[36:37]
	v_lshlrev_b32_e32 v0, 10, v34
	v_lshl_add_u64 v[36:37], s[92:93], 0, v[36:37]
	v_and_b32_e32 v0, 0x3fc00, v0
	v_lshl_add_u64 v[36:37], v[36:37], 0, v[0:1]
	v_lshl_add_u64 v[36:37], s[62:63], 2, v[36:37]
	v_lshl_add_u64 v[36:37], v[158:159], 2, v[36:37]
	global_store_dwordx4 v[36:37], v[30:33], off
	global_store_dwordx4 v[36:37], v[26:29], off offset:64
	global_store_dwordx4 v[36:37], v[22:25], off offset:128
	global_store_dwordx4 v[36:37], v[18:21], off offset:192
	s_and_b64 vcc, exec, s[40:41]
	s_cbranch_vccnz .LBB0_926
	s_branch .LBB0_925

.LBB0_926:
	v_ashrrev_i32_e32 v35, 31, v34
	s_and_b64 vcc, exec, s[44:45]
	s_mov_b64 s[0:1], -1
	s_cbranch_vccnz .LBB0_928
	v_mov_b64_e32 v[36:37], s[18:19]
	v_lshrrev_b32_e32 v244, 2, v34
	v_and_b32_e32 v245, 3, v34
	v_lshlrev_b32_e32 v244, 11, v244
	v_lshl_or_b32 v244, v245, 4, v244
	v_lshrrev_b32_e32 v245, 3, v158
	v_mul_u32_u24_e32 v245, 48, v245
	v_add_u32_e32 v244, v244, v245
	v_mov_b32_e32 v245, 0
	v_lshl_add_u64 v[36:37], v[36:37], 0, v[244:245]
	v_lshl_add_u64 v[36:37], s[62:63], 3, v[36:37]
	s_mov_b64 s[100:101], 0x60
	s_cbranch_execz .LBB0_929
	s_branch .LBB0_930

.LBB0_929:
	v_lshlrev_b64 v[34:35], 11, v[34:35]
	v_lshl_add_u64 v[34:35], s[16:17], 0, v[34:35]
	v_lshl_add_u64 v[36:37], s[64:65], 1, v[34:35]
	s_mov_b64 s[100:101], 0
	v_pk_mul_f32 v[32:33], v[32:33], s[6:7] op_sel_hi:[1,0]
	v_pk_mul_f32 v[30:31], v[30:31], s[6:7] op_sel_hi:[1,0]
	v_pk_mul_f32 v[28:29], v[28:29], s[6:7] op_sel_hi:[1,0]
	v_pk_mul_f32 v[26:27], v[26:27], s[6:7] op_sel_hi:[1,0]
	v_pk_mul_f32 v[24:25], v[24:25], s[6:7] op_sel_hi:[1,0]
	v_pk_mul_f32 v[22:23], v[22:23], s[6:7] op_sel_hi:[1,0]
	v_pk_mul_f32 v[20:21], v[20:21], s[6:7] op_sel_hi:[1,0]
	v_pk_mul_f32 v[18:19], v[18:19], s[6:7] op_sel_hi:[1,0]
.LBB0_930:
	v_lshl_add_u64 v[34:35], v[158:159], 1, v[36:37]
	v_lshl_add_u64 v[238:239], v[34:35], 0, s[100:101]
	v_lshl_add_u64 v[240:241], v[238:239], 0, s[100:101]
	v_lshl_add_u64 v[242:243], v[240:241], 0, s[100:101]
	v_cvt_pk_bf16_f32 v18, v18, v19
	v_cvt_pk_bf16_f32 v19, v20, v21
	v_cvt_pk_bf16_f32 v22, v22, v23
	v_cvt_pk_bf16_f32 v23, v24, v25
	global_store_dwordx2 v[242:243], v[18:19], off offset:96
	v_pk_mul_f32 v[18:19], v[16:17], v[16:17]
	v_pk_mul_f32 v[20:21], v[14:15], v[14:15]
	global_store_dwordx2 v[240:241], v[22:23], off offset:64
	v_pk_mov_b32 v[22:23], v[20:21], v[18:19] op_sel:[1,0]
	v_mov_b32_e32 v21, v19
	v_pk_add_f32 v[18:19], v[22:23], v[20:21]
	v_pk_mul_f32 v[20:21], v[12:13], v[12:13]
	v_pk_mul_f32 v[22:23], v[10:11], v[10:11]
	v_mul_f32_e32 v0, v2, v2
	v_pk_mov_b32 v[24:25], v[22:23], v[20:21] op_sel:[1,0]
	v_mov_b32_e32 v23, v21
	v_pk_add_f32 v[20:21], v[24:25], v[22:23]
	v_mul_f32_e32 v22, v3, v3
	v_pk_add_f32 v[18:19], v[18:19], v[18:19] op_sel:[0,1] op_sel_hi:[1,0]
	v_pk_add_f32 v[20:21], v[20:21], v[20:21] op_sel:[0,1] op_sel_hi:[1,0]
	v_mov_b32_e32 v19, v0
	v_mov_b32_e32 v21, v22
	v_mul_f32_e32 v0, v7, v7
	v_mul_f32_e32 v23, v4, v4
	v_pk_add_f32 v[18:19], v[18:19], v[20:21]
	v_pk_fma_f32 v[20:21], v[6:7], v[6:7], v[0:1] op_sel_hi:[1,1,0]
	v_mul_f32_e32 v0, v9, v9
	v_mul_f32_e32 v24, v5, v5
	v_mov_b32_e32 v21, v23
	v_pk_fma_f32 v[22:23], v[8:9], v[8:9], v[0:1] op_sel_hi:[1,1,0]
	v_cvt_pk_bf16_f32 v30, v30, v31
	v_mov_b32_e32 v23, v24
	v_pk_add_f32 v[20:21], v[20:21], v[22:23]
	v_cvt_pk_bf16_f32 v31, v32, v33
	v_pk_add_f32 v[18:19], v[18:19], v[20:21]
	v_cvt_pk_bf16_f32 v26, v26, v27
	v_add_f32_e32 v0, v18, v19
	ds_bpermute_b32 v18, v174, v0
	v_cvt_pk_bf16_f32 v27, v28, v29
	global_store_dwordx2 v[34:35], v[30:31], off
	global_store_dwordx2 v[238:239], v[26:27], off offset:32
	s_waitcnt lgkmcnt(0)
	v_add_f32_e32 v0, v0, v18
	ds_bpermute_b32 v18, v175, v0
	s_waitcnt lgkmcnt(0)
	v_add_f32_e32 v0, v0, v18
	v_fmamk_f32 v0, v0, 0x3c800000, v187
	v_cmp_gt_f32_e32 vcc, s3, v0
	v_mul_f32_e32 v18, 0x4f800000, v0
	s_nop 0
	v_cndmask_b32_e32 v0, v0, v18, vcc
	v_sqrt_f32_e32 v18, v0
	s_nop 0
	v_add_u32_e32 v19, -1, v18
	v_fma_f32 v20, -v19, v18, v0
	v_cmp_ge_f32_e64 s[0:1], 0, v20
	v_add_u32_e32 v20, 1, v18
	s_nop 0
	v_cndmask_b32_e64 v19, v18, v19, s[0:1]
	v_fma_f32 v18, -v20, v18, v0
	v_cmp_lt_f32_e64 s[0:1], 0, v18
	s_nop 1
	v_cndmask_b32_e64 v18, v19, v20, s[0:1]
	v_mul_f32_e32 v19, 0x37800000, v18
	v_cndmask_b32_e32 v18, v18, v19, vcc
	v_cmp_class_f32_e32 vcc, v0, v202
	s_nop 1
	v_cndmask_b32_e32 v0, v18, v0, vcc
	v_div_scale_f32 v18, s[0:1], v0, v0, 1.0
	v_rcp_f32_e32 v19, v18
	s_nop 0
	v_fma_f32 v20, -v18, v19, 1.0
	v_fmac_f32_e32 v19, v20, v19
	v_div_scale_f32 v20, vcc, 1.0, v0, 1.0
	v_mul_f32_e32 v21, v20, v19
	v_fma_f32 v22, -v18, v21, v20
	v_fmac_f32_e32 v21, v22, v19
	v_fma_f32 v18, -v18, v21, v20
	v_div_fmas_f32 v18, v18, v19, v21
	v_div_fixup_f32 v0, v18, v0, 1.0
	v_pk_mul_f32 v[14:15], v[14:15], v[0:1] op_sel_hi:[1,0]
	v_pk_mul_f32 v[16:17], v[16:17], v[0:1] op_sel_hi:[1,0]
	v_pk_mul_f32 v[10:11], v[10:11], v[0:1] op_sel_hi:[1,0]
	v_pk_mul_f32 v[12:13], v[12:13], v[0:1] op_sel_hi:[1,0]
	v_pk_mul_f32 v[6:7], v[6:7], v[0:1] op_sel_hi:[1,0]
	v_pk_mul_f32 v[8:9], v[8:9], v[0:1] op_sel_hi:[1,0]
	v_pk_mul_f32 v[2:3], v[2:3], v[0:1] op_sel_hi:[1,0]
	v_pk_mul_f32 v[4:5], v[4:5], v[0:1] op_sel_hi:[1,0]
	v_pk_mul_f32 v[16:17], v[80:81], v[16:17]
	v_pk_mul_f32 v[14:15], v[78:79], v[14:15]
	v_pk_mul_f32 v[12:13], v[76:77], v[12:13]
	v_pk_mul_f32 v[10:11], v[74:75], v[10:11]
	v_pk_mul_f32 v[8:9], v[72:73], v[8:9]
	v_pk_mul_f32 v[6:7], v[70:71], v[6:7]
	v_pk_mul_f32 v[4:5], v[68:69], v[4:5]
	v_pk_mul_f32 v[2:3], v[66:67], v[2:3]
	v_add_u32_e32 v18, 0xb0, v164
	s_and_b64 vcc, exec, s[42:43]
	s_cbranch_vccnz .LBB0_932
	v_ashrrev_i32_e32 v20, 8, v18
	v_ashrrev_i32_e32 v21, 31, v20
	v_lshlrev_b64 v[20:21], 19, v[20:21]
	v_lshlrev_b32_e32 v0, 10, v18
	v_lshl_add_u64 v[20:21], s[92:93], 0, v[20:21]
	v_and_b32_e32 v0, 0x3fc00, v0
	v_lshl_add_u64 v[20:21], v[20:21], 0, v[0:1]
	v_lshl_add_u64 v[20:21], s[62:63], 2, v[20:21]
	v_lshl_add_u64 v[20:21], v[158:159], 2, v[20:21]
	global_store_dwordx4 v[20:21], v[14:17], off
	global_store_dwordx4 v[20:21], v[10:13], off offset:64
	global_store_dwordx4 v[20:21], v[6:9], off offset:128
	global_store_dwordx4 v[20:21], v[2:5], off offset:192
	s_and_b64 vcc, exec, s[40:41]
	s_cbranch_vccnz .LBB0_934
	s_branch .LBB0_933

.LBB0_934:
	v_ashrrev_i32_e32 v19, 31, v18
	s_and_b64 vcc, exec, s[44:45]
	s_mov_b64 s[0:1], -1
	s_cbranch_vccnz .LBB0_936
	v_mov_b64_e32 v[20:21], s[18:19]
	v_lshrrev_b32_e32 v244, 2, v18
	v_and_b32_e32 v245, 3, v18
	v_lshlrev_b32_e32 v244, 11, v244
	v_lshl_or_b32 v244, v245, 4, v244
	v_lshrrev_b32_e32 v245, 3, v158
	v_mul_u32_u24_e32 v245, 48, v245
	v_add_u32_e32 v244, v244, v245
	v_mov_b32_e32 v245, 0
	v_lshl_add_u64 v[20:21], v[20:21], 0, v[244:245]
	v_lshl_add_u64 v[20:21], s[62:63], 3, v[20:21]
	s_mov_b64 s[100:101], 0x60
	s_cbranch_execz .LBB0_937
	s_branch .LBB0_938

.LBB0_937:
	v_lshlrev_b64 v[18:19], 11, v[18:19]
	v_lshl_add_u64 v[18:19], s[16:17], 0, v[18:19]
	v_lshl_add_u64 v[20:21], s[64:65], 1, v[18:19]
	s_mov_b64 s[100:101], 0
	v_pk_mul_f32 v[16:17], v[16:17], s[6:7] op_sel_hi:[1,0]
	v_pk_mul_f32 v[14:15], v[14:15], s[6:7] op_sel_hi:[1,0]
	v_pk_mul_f32 v[12:13], v[12:13], s[6:7] op_sel_hi:[1,0]
	v_pk_mul_f32 v[10:11], v[10:11], s[6:7] op_sel_hi:[1,0]
	v_pk_mul_f32 v[8:9], v[8:9], s[6:7] op_sel_hi:[1,0]
	v_pk_mul_f32 v[6:7], v[6:7], s[6:7] op_sel_hi:[1,0]
	v_pk_mul_f32 v[4:5], v[4:5], s[6:7] op_sel_hi:[1,0]
	v_pk_mul_f32 v[2:3], v[2:3], s[6:7] op_sel_hi:[1,0]
.LBB0_938:
	v_lshl_add_u64 v[18:19], v[158:159], 1, v[20:21]
	v_lshl_add_u64 v[238:239], v[18:19], 0, s[100:101]
	v_lshl_add_u64 v[240:241], v[238:239], 0, s[100:101]
	v_lshl_add_u64 v[242:243], v[240:241], 0, s[100:101]
	v_cvt_pk_bf16_f32 v14, v14, v15
	v_cvt_pk_bf16_f32 v15, v16, v17
	v_cvt_pk_bf16_f32 v10, v10, v11
	v_cvt_pk_bf16_f32 v11, v12, v13
	v_cvt_pk_bf16_f32 v6, v6, v7
	v_cvt_pk_bf16_f32 v7, v8, v9
	v_cvt_pk_bf16_f32 v2, v2, v3
	v_cvt_pk_bf16_f32 v3, v4, v5
	global_store_dwordx2 v[18:19], v[14:15], off
	global_store_dwordx2 v[238:239], v[10:11], off offset:32
	global_store_dwordx2 v[240:241], v[6:7], off offset:64
	global_store_dwordx2 v[242:243], v[2:3], off offset:96
	s_and_b64 vcc, exec, s[94:95]
	s_mov_b64 s[0:1], -1
	s_cbranch_vccnz .LBB0_859
	s_branch .LBB0_977

.LBB0_940:
	v_and_b32_e32 v0, s8, v68
	v_lshlrev_b32_e32 v0, 1, v0
	v_lshrrev_b32_e32 v70, 1, v160
	v_add_u32_e32 v69, s0, v158
	v_and_b32_e32 v0, 8, v0
	v_bitop3_b32 v71, s8, v206, v68 bitop3:0x80
	v_and_b32_e32 v70, 4, v70
	v_or3_b32 v0, v71, v0, v70
	v_and_b32_e32 v246, 15, v0
	v_lshrrev_b32_e32 v0, 4, v0
	v_lshl_or_b32 v0, v0, 12, v246
	v_lshl_add_u64 v[66:67], v[66:67], 1, s[20:21]
	v_mad_i64_i32 v[72:73], s[40:41], 16, v69, 0
	v_lshl_add_u64 v[66:67], v[72:73], 1, v[66:67]
	v_lshlrev_b32_e32 v0, 1, v0
	v_lshl_add_u64 v[66:67], v[66:67], 0, v[0:1]
	v_cvt_pk_bf16_f32 v0, v142, s0
	s_movk_i32 s8, 32
	global_store_short v[66:67], v0, off
	v_cvt_pk_bf16_f32 v0, v143, s0
	v_lshl_add_u64 v[66:67], v[66:67], 0, s[8:9]
	global_store_short v[66:67], v0, off
	v_cvt_pk_bf16_f32 v0, v144, s0
	v_lshl_add_u64 v[66:67], v[66:67], 0, s[8:9]
	global_store_short v[66:67], v0, off
	v_cvt_pk_bf16_f32 v0, v145, s0
	v_lshl_add_u64 v[66:67], v[66:67], 0, s[8:9]
	s_movk_i32 s34, 0x1a0
	s_mov_b32 s35, s9
	global_store_short v[66:67], v0, off
	v_cvt_pk_bf16_f32 v0, v138, s0
	v_lshl_add_u64 v[66:67], v[66:67], 0, s[34:35]
	global_store_short v[66:67], v0, off
	v_cvt_pk_bf16_f32 v0, v139, s0
	v_lshl_add_u64 v[66:67], v[66:67], 0, s[8:9]
	global_store_short v[66:67], v0, off
	v_cvt_pk_bf16_f32 v0, v140, s0
	v_lshl_add_u64 v[66:67], v[66:67], 0, s[8:9]
	global_store_short v[66:67], v0, off
	v_cvt_pk_bf16_f32 v0, v141, s0
	v_lshl_add_u64 v[66:67], v[66:67], 0, s[8:9]
	global_store_short v[66:67], v0, off
	v_cvt_pk_bf16_f32 v0, v134, s0
	v_lshl_add_u64 v[66:67], v[66:67], 0, s[34:35]
	global_store_short v[66:67], v0, off
	v_cvt_pk_bf16_f32 v0, v135, s0
	v_lshl_add_u64 v[66:67], v[66:67], 0, s[8:9]
	global_store_short v[66:67], v0, off
	v_cvt_pk_bf16_f32 v0, v136, s0
	v_lshl_add_u64 v[66:67], v[66:67], 0, s[8:9]
	global_store_short v[66:67], v0, off
	v_cvt_pk_bf16_f32 v0, v137, s0
	v_lshl_add_u64 v[66:67], v[66:67], 0, s[8:9]
	global_store_short v[66:67], v0, off
	v_cvt_pk_bf16_f32 v0, v130, s0
	v_lshl_add_u64 v[66:67], v[66:67], 0, s[34:35]
	global_store_short v[66:67], v0, off
	v_cvt_pk_bf16_f32 v0, v131, s0
	v_lshl_add_u64 v[66:67], v[66:67], 0, s[8:9]
	global_store_short v[66:67], v0, off
	v_cvt_pk_bf16_f32 v0, v132, s0
	v_lshl_add_u64 v[66:67], v[66:67], 0, s[8:9]
	global_store_short v[66:67], v0, off
	v_cvt_pk_bf16_f32 v0, v133, s0
	v_lshl_add_u64 v[66:67], v[66:67], 0, s[8:9]
	global_store_short v[66:67], v0, off
	v_cndmask_b32_e64 v0, 0, 1, s[30:31]
	v_add_u32_e32 v71, 16, v68
	v_cmp_ne_u32_e64 s[40:41], 1, v0
	s_andn2_b64 vcc, exec, s[30:31]
	s_mov_b64 s[30:31], -1
	s_cbranch_vccnz .LBB0_942
	v_ashrrev_i32_e32 v66, 8, v71
	v_ashrrev_i32_e32 v67, 31, v66
	v_lshlrev_b64 v[72:73], 19, v[66:67]
	v_lshlrev_b32_e32 v0, 10, v71
	v_lshl_add_u64 v[72:73], s[12:13], 0, v[72:73]
	v_and_b32_e32 v0, 0x3fc00, v0
	v_lshl_add_u64 v[72:73], v[72:73], 0, v[0:1]
	v_lshl_add_u64 v[72:73], s[0:1], 2, v[72:73]
	v_lshl_add_u64 v[72:73], v[158:159], 2, v[72:73]
	v_mul_hi_i32_i24_e32 v67, 0x12000, v66
	v_mul_i32_i24_e32 v66, 0x12000, v66
	s_mov_b64 s[30:31], 0
	global_store_dwordx4 v[72:73], v[126:129], off
	global_store_dwordx4 v[72:73], v[122:125], off offset:64
	global_store_dwordx4 v[72:73], v[118:121], off offset:128
	global_store_dwordx4 v[72:73], v[114:117], off offset:192

.LBB0_945:
	v_and_b32_e32 v0, s8, v71
	v_lshlrev_b32_e32 v0, 1, v0
	v_and_b32_e32 v0, 8, v0
	v_bitop3_b32 v71, s8, v206, v71 bitop3:0x80
	v_or3_b32 v0, v71, v0, v70
	v_and_b32_e32 v246, 15, v0
	v_lshrrev_b32_e32 v0, 4, v0
	v_lshl_or_b32 v0, v0, 12, v246
	v_lshl_add_u64 v[66:67], v[66:67], 1, s[20:21]
	v_mad_i64_i32 v[72:73], s[34:35], 16, v69, 0
	v_lshl_add_u64 v[66:67], v[72:73], 1, v[66:67]
	v_lshlrev_b32_e32 v0, 1, v0
	v_lshl_add_u64 v[66:67], v[66:67], 0, v[0:1]
	v_cvt_pk_bf16_f32 v0, v126, s0
	s_movk_i32 s8, 32
	global_store_short v[66:67], v0, off
	v_cvt_pk_bf16_f32 v0, v127, s0
	v_lshl_add_u64 v[66:67], v[66:67], 0, s[8:9]
	global_store_short v[66:67], v0, off
	v_cvt_pk_bf16_f32 v0, v128, s0
	v_lshl_add_u64 v[66:67], v[66:67], 0, s[8:9]
	global_store_short v[66:67], v0, off
	v_cvt_pk_bf16_f32 v0, v129, s0
	v_lshl_add_u64 v[66:67], v[66:67], 0, s[8:9]
	s_movk_i32 s30, 0x1a0
	s_mov_b32 s31, s9
	global_store_short v[66:67], v0, off
	v_cvt_pk_bf16_f32 v0, v122, s0
	v_lshl_add_u64 v[66:67], v[66:67], 0, s[30:31]
	global_store_short v[66:67], v0, off
	v_cvt_pk_bf16_f32 v0, v123, s0
	v_lshl_add_u64 v[66:67], v[66:67], 0, s[8:9]
	global_store_short v[66:67], v0, off
	v_cvt_pk_bf16_f32 v0, v124, s0
	v_lshl_add_u64 v[66:67], v[66:67], 0, s[8:9]
	global_store_short v[66:67], v0, off
	v_cvt_pk_bf16_f32 v0, v125, s0
	v_lshl_add_u64 v[66:67], v[66:67], 0, s[8:9]
	global_store_short v[66:67], v0, off
	v_cvt_pk_bf16_f32 v0, v118, s0
	v_lshl_add_u64 v[66:67], v[66:67], 0, s[30:31]
	global_store_short v[66:67], v0, off
	v_cvt_pk_bf16_f32 v0, v119, s0
	v_lshl_add_u64 v[66:67], v[66:67], 0, s[8:9]
	global_store_short v[66:67], v0, off
	v_cvt_pk_bf16_f32 v0, v120, s0
	v_lshl_add_u64 v[66:67], v[66:67], 0, s[8:9]
	global_store_short v[66:67], v0, off
	v_cvt_pk_bf16_f32 v0, v121, s0
	v_lshl_add_u64 v[66:67], v[66:67], 0, s[8:9]
	global_store_short v[66:67], v0, off
	v_cvt_pk_bf16_f32 v0, v114, s0
	v_lshl_add_u64 v[66:67], v[66:67], 0, s[30:31]
	global_store_short v[66:67], v0, off
	v_cvt_pk_bf16_f32 v0, v115, s0
	v_lshl_add_u64 v[66:67], v[66:67], 0, s[8:9]
	global_store_short v[66:67], v0, off
	v_cvt_pk_bf16_f32 v0, v116, s0
	v_lshl_add_u64 v[66:67], v[66:67], 0, s[8:9]
	global_store_short v[66:67], v0, off
	v_cvt_pk_bf16_f32 v0, v117, s0
	v_lshl_add_u64 v[66:67], v[66:67], 0, s[8:9]
	v_add_u32_e32 v71, 32, v68
	s_and_b64 vcc, exec, s[40:41]
	s_mov_b64 s[30:31], -1
	global_store_short v[66:67], v0, off
	s_cbranch_vccnz .LBB0_947
	v_ashrrev_i32_e32 v66, 8, v71
	v_ashrrev_i32_e32 v67, 31, v66
	v_lshlrev_b64 v[72:73], 19, v[66:67]
	v_lshlrev_b32_e32 v0, 10, v71
	v_lshl_add_u64 v[72:73], s[12:13], 0, v[72:73]
	v_and_b32_e32 v0, 0x3fc00, v0
	v_lshl_add_u64 v[72:73], v[72:73], 0, v[0:1]
	v_lshl_add_u64 v[72:73], s[0:1], 2, v[72:73]
	v_lshl_add_u64 v[72:73], v[158:159], 2, v[72:73]
	v_mul_hi_i32_i24_e32 v67, 0x12000, v66
	v_mul_i32_i24_e32 v66, 0x12000, v66
	s_mov_b64 s[30:31], 0
	global_store_dwordx4 v[72:73], v[110:113], off
	global_store_dwordx4 v[72:73], v[106:109], off offset:64
	global_store_dwordx4 v[72:73], v[102:105], off offset:128
	global_store_dwordx4 v[72:73], v[98:101], off offset:192

.LBB0_950:
	v_and_b32_e32 v0, s8, v71
	v_lshlrev_b32_e32 v0, 1, v0
	v_and_b32_e32 v0, 8, v0
	v_bitop3_b32 v71, s8, v206, v71 bitop3:0x80
	v_or3_b32 v0, v71, v0, v70
	v_and_b32_e32 v246, 15, v0
	v_lshrrev_b32_e32 v0, 4, v0
	v_lshl_or_b32 v0, v0, 12, v246
	v_lshl_add_u64 v[66:67], v[66:67], 1, s[20:21]
	v_mad_i64_i32 v[72:73], s[34:35], 16, v69, 0
	v_lshl_add_u64 v[66:67], v[72:73], 1, v[66:67]
	v_lshlrev_b32_e32 v0, 1, v0
	v_lshl_add_u64 v[66:67], v[66:67], 0, v[0:1]
	v_cvt_pk_bf16_f32 v0, v110, s0
	s_movk_i32 s8, 32
	global_store_short v[66:67], v0, off
	v_cvt_pk_bf16_f32 v0, v111, s0
	v_lshl_add_u64 v[66:67], v[66:67], 0, s[8:9]
	global_store_short v[66:67], v0, off
	v_cvt_pk_bf16_f32 v0, v112, s0
	v_lshl_add_u64 v[66:67], v[66:67], 0, s[8:9]
	global_store_short v[66:67], v0, off
	v_cvt_pk_bf16_f32 v0, v113, s0
	v_lshl_add_u64 v[66:67], v[66:67], 0, s[8:9]
	s_movk_i32 s30, 0x1a0
	s_mov_b32 s31, s9
	global_store_short v[66:67], v0, off
	v_cvt_pk_bf16_f32 v0, v106, s0
	v_lshl_add_u64 v[66:67], v[66:67], 0, s[30:31]
	global_store_short v[66:67], v0, off
	v_cvt_pk_bf16_f32 v0, v107, s0
	v_lshl_add_u64 v[66:67], v[66:67], 0, s[8:9]
	global_store_short v[66:67], v0, off
	v_cvt_pk_bf16_f32 v0, v108, s0
	v_lshl_add_u64 v[66:67], v[66:67], 0, s[8:9]
	global_store_short v[66:67], v0, off
	v_cvt_pk_bf16_f32 v0, v109, s0
	v_lshl_add_u64 v[66:67], v[66:67], 0, s[8:9]
	global_store_short v[66:67], v0, off
	v_cvt_pk_bf16_f32 v0, v102, s0
	v_lshl_add_u64 v[66:67], v[66:67], 0, s[30:31]
	global_store_short v[66:67], v0, off
	v_cvt_pk_bf16_f32 v0, v103, s0
	v_lshl_add_u64 v[66:67], v[66:67], 0, s[8:9]
	global_store_short v[66:67], v0, off
	v_cvt_pk_bf16_f32 v0, v104, s0
	v_lshl_add_u64 v[66:67], v[66:67], 0, s[8:9]
	global_store_short v[66:67], v0, off
	v_cvt_pk_bf16_f32 v0, v105, s0
	v_lshl_add_u64 v[66:67], v[66:67], 0, s[8:9]
	global_store_short v[66:67], v0, off
	v_cvt_pk_bf16_f32 v0, v98, s0
	v_lshl_add_u64 v[66:67], v[66:67], 0, s[30:31]
	global_store_short v[66:67], v0, off
	v_cvt_pk_bf16_f32 v0, v99, s0
	v_lshl_add_u64 v[66:67], v[66:67], 0, s[8:9]
	global_store_short v[66:67], v0, off
	v_cvt_pk_bf16_f32 v0, v100, s0
	v_lshl_add_u64 v[66:67], v[66:67], 0, s[8:9]
	global_store_short v[66:67], v0, off
	v_cvt_pk_bf16_f32 v0, v101, s0
	v_lshl_add_u64 v[66:67], v[66:67], 0, s[8:9]
	v_add_u32_e32 v71, 48, v68
	s_and_b64 vcc, exec, s[40:41]
	s_mov_b64 s[30:31], -1
	global_store_short v[66:67], v0, off
	s_cbranch_vccnz .LBB0_952
	v_ashrrev_i32_e32 v66, 8, v71
	v_ashrrev_i32_e32 v67, 31, v66
	v_lshlrev_b64 v[72:73], 19, v[66:67]
	v_lshlrev_b32_e32 v0, 10, v71
	v_lshl_add_u64 v[72:73], s[12:13], 0, v[72:73]
	v_and_b32_e32 v0, 0x3fc00, v0
	v_lshl_add_u64 v[72:73], v[72:73], 0, v[0:1]
	v_lshl_add_u64 v[72:73], s[0:1], 2, v[72:73]
	v_lshl_add_u64 v[72:73], v[158:159], 2, v[72:73]
	v_mul_hi_i32_i24_e32 v67, 0x12000, v66
	v_mul_i32_i24_e32 v66, 0x12000, v66
	s_mov_b64 s[30:31], 0
	global_store_dwordx4 v[72:73], v[94:97], off
	global_store_dwordx4 v[72:73], v[90:93], off offset:64
	global_store_dwordx4 v[72:73], v[86:89], off offset:128
	global_store_dwordx4 v[72:73], v[82:85], off offset:192

.LBB0_955:
	v_and_b32_e32 v0, s8, v71
	v_lshlrev_b32_e32 v0, 1, v0
	v_and_b32_e32 v0, 8, v0
	v_bitop3_b32 v71, s8, v206, v71 bitop3:0x80
	v_or3_b32 v0, v71, v0, v70
	v_and_b32_e32 v246, 15, v0
	v_lshrrev_b32_e32 v0, 4, v0
	v_lshl_or_b32 v0, v0, 12, v246
	v_lshl_add_u64 v[66:67], v[66:67], 1, s[20:21]
	v_mad_i64_i32 v[72:73], s[34:35], 16, v69, 0
	v_lshl_add_u64 v[66:67], v[72:73], 1, v[66:67]
	v_lshlrev_b32_e32 v0, 1, v0
	v_lshl_add_u64 v[66:67], v[66:67], 0, v[0:1]
	v_cvt_pk_bf16_f32 v0, v94, s0
	s_movk_i32 s8, 32
	global_store_short v[66:67], v0, off
	v_cvt_pk_bf16_f32 v0, v95, s0
	v_lshl_add_u64 v[66:67], v[66:67], 0, s[8:9]
	global_store_short v[66:67], v0, off
	v_cvt_pk_bf16_f32 v0, v96, s0
	v_lshl_add_u64 v[66:67], v[66:67], 0, s[8:9]
	global_store_short v[66:67], v0, off
	v_cvt_pk_bf16_f32 v0, v97, s0
	v_lshl_add_u64 v[66:67], v[66:67], 0, s[8:9]
	s_movk_i32 s30, 0x1a0
	s_mov_b32 s31, s9
	global_store_short v[66:67], v0, off
	v_cvt_pk_bf16_f32 v0, v90, s0
	v_lshl_add_u64 v[66:67], v[66:67], 0, s[30:31]
	global_store_short v[66:67], v0, off
	v_cvt_pk_bf16_f32 v0, v91, s0
	v_lshl_add_u64 v[66:67], v[66:67], 0, s[8:9]
	global_store_short v[66:67], v0, off
	v_cvt_pk_bf16_f32 v0, v92, s0
	v_lshl_add_u64 v[66:67], v[66:67], 0, s[8:9]
	global_store_short v[66:67], v0, off
	v_cvt_pk_bf16_f32 v0, v93, s0
	v_lshl_add_u64 v[66:67], v[66:67], 0, s[8:9]
	global_store_short v[66:67], v0, off
	v_cvt_pk_bf16_f32 v0, v86, s0
	v_lshl_add_u64 v[66:67], v[66:67], 0, s[30:31]
	global_store_short v[66:67], v0, off
	v_cvt_pk_bf16_f32 v0, v87, s0
	v_lshl_add_u64 v[66:67], v[66:67], 0, s[8:9]
	global_store_short v[66:67], v0, off
	v_cvt_pk_bf16_f32 v0, v88, s0
	v_lshl_add_u64 v[66:67], v[66:67], 0, s[8:9]
	global_store_short v[66:67], v0, off
	v_cvt_pk_bf16_f32 v0, v89, s0
	v_lshl_add_u64 v[66:67], v[66:67], 0, s[8:9]
	global_store_short v[66:67], v0, off
	v_cvt_pk_bf16_f32 v0, v82, s0
	v_lshl_add_u64 v[66:67], v[66:67], 0, s[30:31]
	global_store_short v[66:67], v0, off
	v_cvt_pk_bf16_f32 v0, v83, s0
	v_lshl_add_u64 v[66:67], v[66:67], 0, s[8:9]
	global_store_short v[66:67], v0, off
	v_cvt_pk_bf16_f32 v0, v84, s0
	v_lshl_add_u64 v[66:67], v[66:67], 0, s[8:9]
	global_store_short v[66:67], v0, off
	v_cvt_pk_bf16_f32 v0, v85, s0
	v_lshl_add_u64 v[66:67], v[66:67], 0, s[8:9]
	v_add_u32_e32 v71, 0x80, v68
	s_and_b64 vcc, exec, s[40:41]
	s_mov_b64 s[30:31], -1
	global_store_short v[66:67], v0, off
	s_cbranch_vccnz .LBB0_957
	v_ashrrev_i32_e32 v66, 8, v71
	v_ashrrev_i32_e32 v67, 31, v66
	v_lshlrev_b64 v[72:73], 19, v[66:67]
	v_lshlrev_b32_e32 v0, 10, v71
	v_lshl_add_u64 v[72:73], s[12:13], 0, v[72:73]
	v_and_b32_e32 v0, 0x3fc00, v0
	v_lshl_add_u64 v[72:73], v[72:73], 0, v[0:1]
	v_lshl_add_u64 v[72:73], s[0:1], 2, v[72:73]
	v_lshl_add_u64 v[72:73], v[158:159], 2, v[72:73]
	v_mul_hi_i32_i24_e32 v67, 0x12000, v66
	v_mul_i32_i24_e32 v66, 0x12000, v66
	s_mov_b64 s[30:31], 0
	global_store_dwordx4 v[72:73], v[62:65], off
	global_store_dwordx4 v[72:73], v[58:61], off offset:64
	global_store_dwordx4 v[72:73], v[54:57], off offset:128
	global_store_dwordx4 v[72:73], v[50:53], off offset:192

.LBB0_960:
	v_and_b32_e32 v0, s8, v71
	v_lshlrev_b32_e32 v0, 1, v0
	v_and_b32_e32 v0, 8, v0
	v_bitop3_b32 v71, s8, v206, v71 bitop3:0x80
	v_or3_b32 v0, v71, v0, v70
	v_and_b32_e32 v246, 15, v0
	v_lshrrev_b32_e32 v0, 4, v0
	v_lshl_or_b32 v0, v0, 12, v246
	v_lshl_add_u64 v[66:67], v[66:67], 1, s[20:21]
	v_mad_i64_i32 v[72:73], s[34:35], 16, v69, 0
	v_lshl_add_u64 v[66:67], v[72:73], 1, v[66:67]
	v_lshlrev_b32_e32 v0, 1, v0
	v_lshl_add_u64 v[66:67], v[66:67], 0, v[0:1]
	v_cvt_pk_bf16_f32 v0, v62, s0
	s_movk_i32 s8, 32
	global_store_short v[66:67], v0, off
	v_cvt_pk_bf16_f32 v0, v63, s0
	v_lshl_add_u64 v[66:67], v[66:67], 0, s[8:9]
	global_store_short v[66:67], v0, off
	v_cvt_pk_bf16_f32 v0, v64, s0
	v_lshl_add_u64 v[66:67], v[66:67], 0, s[8:9]
	global_store_short v[66:67], v0, off
	v_cvt_pk_bf16_f32 v0, v65, s0
	v_lshl_add_u64 v[66:67], v[66:67], 0, s[8:9]
	s_movk_i32 s30, 0x1a0
	s_mov_b32 s31, s9
	global_store_short v[66:67], v0, off
	v_cvt_pk_bf16_f32 v0, v58, s0
	v_lshl_add_u64 v[66:67], v[66:67], 0, s[30:31]
	global_store_short v[66:67], v0, off
	v_cvt_pk_bf16_f32 v0, v59, s0
	v_lshl_add_u64 v[66:67], v[66:67], 0, s[8:9]
	global_store_short v[66:67], v0, off
	v_cvt_pk_bf16_f32 v0, v60, s0
	v_lshl_add_u64 v[66:67], v[66:67], 0, s[8:9]
	global_store_short v[66:67], v0, off
	v_cvt_pk_bf16_f32 v0, v61, s0
	v_lshl_add_u64 v[66:67], v[66:67], 0, s[8:9]
	global_store_short v[66:67], v0, off
	v_cvt_pk_bf16_f32 v0, v54, s0
	v_lshl_add_u64 v[66:67], v[66:67], 0, s[30:31]
	global_store_short v[66:67], v0, off
	v_cvt_pk_bf16_f32 v0, v55, s0
	v_lshl_add_u64 v[66:67], v[66:67], 0, s[8:9]
	global_store_short v[66:67], v0, off
	v_cvt_pk_bf16_f32 v0, v56, s0
	v_lshl_add_u64 v[66:67], v[66:67], 0, s[8:9]
	global_store_short v[66:67], v0, off
	v_cvt_pk_bf16_f32 v0, v57, s0
	v_lshl_add_u64 v[66:67], v[66:67], 0, s[8:9]
	global_store_short v[66:67], v0, off
	v_cvt_pk_bf16_f32 v0, v50, s0
	v_lshl_add_u64 v[66:67], v[66:67], 0, s[30:31]
	global_store_short v[66:67], v0, off
	v_cvt_pk_bf16_f32 v0, v51, s0
	v_lshl_add_u64 v[66:67], v[66:67], 0, s[8:9]
	global_store_short v[66:67], v0, off
	v_cvt_pk_bf16_f32 v0, v52, s0
	v_lshl_add_u64 v[66:67], v[66:67], 0, s[8:9]
	global_store_short v[66:67], v0, off
	v_cvt_pk_bf16_f32 v0, v53, s0
	v_lshl_add_u64 v[66:67], v[66:67], 0, s[8:9]
	v_add_u32_e32 v71, 0x90, v68
	s_and_b64 vcc, exec, s[40:41]
	s_mov_b64 s[30:31], -1
	global_store_short v[66:67], v0, off
	s_cbranch_vccnz .LBB0_962
	v_ashrrev_i32_e32 v66, 8, v71
	v_ashrrev_i32_e32 v67, 31, v66
	v_lshlrev_b64 v[72:73], 19, v[66:67]
	v_lshlrev_b32_e32 v0, 10, v71
	v_lshl_add_u64 v[72:73], s[12:13], 0, v[72:73]
	v_and_b32_e32 v0, 0x3fc00, v0
	v_lshl_add_u64 v[72:73], v[72:73], 0, v[0:1]
	v_lshl_add_u64 v[72:73], s[0:1], 2, v[72:73]
	v_lshl_add_u64 v[72:73], v[158:159], 2, v[72:73]
	v_mul_hi_i32_i24_e32 v67, 0x12000, v66
	v_mul_i32_i24_e32 v66, 0x12000, v66
	s_mov_b64 s[30:31], 0
	global_store_dwordx4 v[72:73], v[46:49], off
	global_store_dwordx4 v[72:73], v[42:45], off offset:64
	global_store_dwordx4 v[72:73], v[38:41], off offset:128
	global_store_dwordx4 v[72:73], v[34:37], off offset:192

.LBB0_965:
	v_and_b32_e32 v0, s8, v71
	v_lshlrev_b32_e32 v0, 1, v0
	v_and_b32_e32 v0, 8, v0
	v_bitop3_b32 v71, s8, v206, v71 bitop3:0x80
	v_or3_b32 v0, v71, v0, v70
	v_and_b32_e32 v246, 15, v0
	v_lshrrev_b32_e32 v0, 4, v0
	v_lshl_or_b32 v0, v0, 12, v246
	v_lshl_add_u64 v[66:67], v[66:67], 1, s[20:21]
	v_mad_i64_i32 v[72:73], s[34:35], 16, v69, 0
	v_lshl_add_u64 v[66:67], v[72:73], 1, v[66:67]
	v_lshlrev_b32_e32 v0, 1, v0
	v_lshl_add_u64 v[66:67], v[66:67], 0, v[0:1]
	v_cvt_pk_bf16_f32 v0, v46, s0
	s_movk_i32 s8, 32
	global_store_short v[66:67], v0, off
	v_cvt_pk_bf16_f32 v0, v47, s0
	v_lshl_add_u64 v[66:67], v[66:67], 0, s[8:9]
	global_store_short v[66:67], v0, off
	v_cvt_pk_bf16_f32 v0, v48, s0
	v_lshl_add_u64 v[66:67], v[66:67], 0, s[8:9]
	global_store_short v[66:67], v0, off
	v_cvt_pk_bf16_f32 v0, v49, s0
	v_lshl_add_u64 v[66:67], v[66:67], 0, s[8:9]
	s_movk_i32 s30, 0x1a0
	s_mov_b32 s31, s9
	global_store_short v[66:67], v0, off
	v_cvt_pk_bf16_f32 v0, v42, s0
	v_lshl_add_u64 v[66:67], v[66:67], 0, s[30:31]
	global_store_short v[66:67], v0, off
	v_cvt_pk_bf16_f32 v0, v43, s0
	v_lshl_add_u64 v[66:67], v[66:67], 0, s[8:9]
	global_store_short v[66:67], v0, off
	v_cvt_pk_bf16_f32 v0, v44, s0
	v_lshl_add_u64 v[66:67], v[66:67], 0, s[8:9]
	global_store_short v[66:67], v0, off
	v_cvt_pk_bf16_f32 v0, v45, s0
	v_lshl_add_u64 v[66:67], v[66:67], 0, s[8:9]
	global_store_short v[66:67], v0, off
	v_cvt_pk_bf16_f32 v0, v38, s0
	v_lshl_add_u64 v[66:67], v[66:67], 0, s[30:31]
	global_store_short v[66:67], v0, off
	v_cvt_pk_bf16_f32 v0, v39, s0
	v_lshl_add_u64 v[66:67], v[66:67], 0, s[8:9]
	global_store_short v[66:67], v0, off
	v_cvt_pk_bf16_f32 v0, v40, s0
	v_lshl_add_u64 v[66:67], v[66:67], 0, s[8:9]
	global_store_short v[66:67], v0, off
	v_cvt_pk_bf16_f32 v0, v41, s0
	v_lshl_add_u64 v[66:67], v[66:67], 0, s[8:9]
	global_store_short v[66:67], v0, off
	v_cvt_pk_bf16_f32 v0, v34, s0
	v_lshl_add_u64 v[66:67], v[66:67], 0, s[30:31]
	global_store_short v[66:67], v0, off
	v_cvt_pk_bf16_f32 v0, v35, s0
	v_lshl_add_u64 v[66:67], v[66:67], 0, s[8:9]
	global_store_short v[66:67], v0, off
	v_cvt_pk_bf16_f32 v0, v36, s0
	v_lshl_add_u64 v[66:67], v[66:67], 0, s[8:9]
	global_store_short v[66:67], v0, off
	v_cvt_pk_bf16_f32 v0, v37, s0
	v_lshl_add_u64 v[66:67], v[66:67], 0, s[8:9]
	v_add_u32_e32 v71, 0xa0, v68
	s_and_b64 vcc, exec, s[40:41]
	s_mov_b64 s[30:31], -1
	global_store_short v[66:67], v0, off
	s_cbranch_vccnz .LBB0_967
	v_ashrrev_i32_e32 v66, 8, v71
	v_ashrrev_i32_e32 v67, 31, v66
	v_lshlrev_b64 v[72:73], 19, v[66:67]
	v_lshlrev_b32_e32 v0, 10, v71
	v_lshl_add_u64 v[72:73], s[12:13], 0, v[72:73]
	v_and_b32_e32 v0, 0x3fc00, v0
	v_lshl_add_u64 v[72:73], v[72:73], 0, v[0:1]
	v_lshl_add_u64 v[72:73], s[0:1], 2, v[72:73]
	v_lshl_add_u64 v[72:73], v[158:159], 2, v[72:73]
	v_mul_hi_i32_i24_e32 v67, 0x12000, v66
	v_mul_i32_i24_e32 v66, 0x12000, v66
	s_mov_b64 s[30:31], 0
	global_store_dwordx4 v[72:73], v[30:33], off
	global_store_dwordx4 v[72:73], v[26:29], off offset:64
	global_store_dwordx4 v[72:73], v[22:25], off offset:128
	global_store_dwordx4 v[72:73], v[18:21], off offset:192

.LBB0_970:
	v_and_b32_e32 v0, s8, v71
	v_lshlrev_b32_e32 v0, 1, v0
	v_and_b32_e32 v0, 8, v0
	v_bitop3_b32 v71, s8, v206, v71 bitop3:0x80
	v_or3_b32 v0, v71, v0, v70
	v_and_b32_e32 v246, 15, v0
	v_lshrrev_b32_e32 v0, 4, v0
	v_lshl_or_b32 v0, v0, 12, v246
	v_lshl_add_u64 v[66:67], v[66:67], 1, s[20:21]
	v_mad_i64_i32 v[72:73], s[34:35], 16, v69, 0
	v_lshl_add_u64 v[66:67], v[72:73], 1, v[66:67]
	v_lshlrev_b32_e32 v0, 1, v0
	v_lshl_add_u64 v[66:67], v[66:67], 0, v[0:1]
	v_cvt_pk_bf16_f32 v0, v30, s0
	s_movk_i32 s8, 32
	global_store_short v[66:67], v0, off
	v_cvt_pk_bf16_f32 v0, v31, s0
	v_lshl_add_u64 v[66:67], v[66:67], 0, s[8:9]
	global_store_short v[66:67], v0, off
	v_cvt_pk_bf16_f32 v0, v32, s0
	v_lshl_add_u64 v[66:67], v[66:67], 0, s[8:9]
	global_store_short v[66:67], v0, off
	v_cvt_pk_bf16_f32 v0, v33, s0
	v_lshl_add_u64 v[66:67], v[66:67], 0, s[8:9]
	s_movk_i32 s30, 0x1a0
	s_mov_b32 s31, s9
	global_store_short v[66:67], v0, off
	v_cvt_pk_bf16_f32 v0, v26, s0
	v_lshl_add_u64 v[66:67], v[66:67], 0, s[30:31]
	global_store_short v[66:67], v0, off
	v_cvt_pk_bf16_f32 v0, v27, s0
	v_lshl_add_u64 v[66:67], v[66:67], 0, s[8:9]
	global_store_short v[66:67], v0, off
	v_cvt_pk_bf16_f32 v0, v28, s0
	v_lshl_add_u64 v[66:67], v[66:67], 0, s[8:9]
	global_store_short v[66:67], v0, off
	v_cvt_pk_bf16_f32 v0, v29, s0
	v_lshl_add_u64 v[66:67], v[66:67], 0, s[8:9]
	global_store_short v[66:67], v0, off
	v_cvt_pk_bf16_f32 v0, v22, s0
	v_lshl_add_u64 v[66:67], v[66:67], 0, s[30:31]
	global_store_short v[66:67], v0, off
	v_cvt_pk_bf16_f32 v0, v23, s0
	v_lshl_add_u64 v[66:67], v[66:67], 0, s[8:9]
	global_store_short v[66:67], v0, off
	v_cvt_pk_bf16_f32 v0, v24, s0
	v_lshl_add_u64 v[66:67], v[66:67], 0, s[8:9]
	global_store_short v[66:67], v0, off
	v_cvt_pk_bf16_f32 v0, v25, s0
	v_lshl_add_u64 v[66:67], v[66:67], 0, s[8:9]
	global_store_short v[66:67], v0, off
	v_cvt_pk_bf16_f32 v0, v18, s0
	v_lshl_add_u64 v[66:67], v[66:67], 0, s[30:31]
	global_store_short v[66:67], v0, off
	v_cvt_pk_bf16_f32 v0, v19, s0
	v_lshl_add_u64 v[66:67], v[66:67], 0, s[8:9]
	global_store_short v[66:67], v0, off
	v_cvt_pk_bf16_f32 v0, v20, s0
	v_lshl_add_u64 v[66:67], v[66:67], 0, s[8:9]
	global_store_short v[66:67], v0, off
	v_cvt_pk_bf16_f32 v0, v21, s0
	v_lshl_add_u64 v[66:67], v[66:67], 0, s[8:9]
	v_add_u32_e32 v71, 0xb0, v68
	s_and_b64 vcc, exec, s[40:41]
	s_mov_b64 s[30:31], -1
	global_store_short v[66:67], v0, off
	s_cbranch_vccnz .LBB0_972
	v_ashrrev_i32_e32 v66, 8, v71
	v_ashrrev_i32_e32 v67, 31, v66
	v_lshlrev_b64 v[72:73], 19, v[66:67]
	v_lshlrev_b32_e32 v0, 10, v71
	v_lshl_add_u64 v[72:73], s[12:13], 0, v[72:73]
	v_and_b32_e32 v0, 0x3fc00, v0
	v_lshl_add_u64 v[72:73], v[72:73], 0, v[0:1]
	v_lshl_add_u64 v[72:73], s[0:1], 2, v[72:73]
	v_lshl_add_u64 v[72:73], v[158:159], 2, v[72:73]
	v_mul_hi_i32_i24_e32 v67, 0x12000, v66
	v_mul_i32_i24_e32 v66, 0x12000, v66
	s_mov_b64 s[30:31], 0
	global_store_dwordx4 v[72:73], v[14:17], off
	global_store_dwordx4 v[72:73], v[10:13], off offset:64
	global_store_dwordx4 v[72:73], v[6:9], off offset:128
	global_store_dwordx4 v[72:73], v[2:5], off offset:192

.LBB0_975:
	v_and_b32_e32 v0, s1, v71
	v_lshlrev_b32_e32 v0, 1, v0
	v_and_b32_e32 v0, 8, v0
	v_bitop3_b32 v68, s1, v206, v71 bitop3:0x80
	v_or3_b32 v0, v68, v0, v70
	v_and_b32_e32 v246, 15, v0
	v_lshrrev_b32_e32 v0, 4, v0
	v_lshl_or_b32 v0, v0, 12, v246
	v_lshl_add_u64 v[66:67], v[66:67], 1, s[20:21]
	v_mad_i64_i32 v[68:69], s[30:31], 16, v69, 0
	v_lshl_add_u64 v[66:67], v[68:69], 1, v[66:67]
	v_lshlrev_b32_e32 v0, 1, v0
	v_lshl_add_u64 v[66:67], v[66:67], 0, v[0:1]
	v_cvt_pk_bf16_f32 v0, v14, s0
	s_movk_i32 s8, 32
	global_store_short v[66:67], v0, off
	v_cvt_pk_bf16_f32 v0, v15, s0
	v_lshl_add_u64 v[66:67], v[66:67], 0, s[8:9]
	global_store_short v[66:67], v0, off
	v_cvt_pk_bf16_f32 v0, v16, s0
	v_lshl_add_u64 v[66:67], v[66:67], 0, s[8:9]
	global_store_short v[66:67], v0, off
	v_cvt_pk_bf16_f32 v0, v17, s0
	v_lshl_add_u64 v[66:67], v[66:67], 0, s[8:9]
	global_store_short v[66:67], v0, off
	v_cvt_pk_bf16_f32 v0, v10, s0
	s_movk_i32 s0, 0x1a0
	s_mov_b32 s1, s9
	v_lshl_add_u64 v[66:67], v[66:67], 0, s[0:1]
	global_store_short v[66:67], v0, off
	v_cvt_pk_bf16_f32 v0, v11, s0
	v_lshl_add_u64 v[66:67], v[66:67], 0, s[8:9]
	global_store_short v[66:67], v0, off
	v_cvt_pk_bf16_f32 v0, v12, s0
	v_lshl_add_u64 v[66:67], v[66:67], 0, s[8:9]
	global_store_short v[66:67], v0, off
	v_cvt_pk_bf16_f32 v0, v13, s0
	v_lshl_add_u64 v[66:67], v[66:67], 0, s[8:9]
	global_store_short v[66:67], v0, off
	v_cvt_pk_bf16_f32 v0, v6, s0
	v_lshl_add_u64 v[66:67], v[66:67], 0, s[0:1]
	global_store_short v[66:67], v0, off
	v_cvt_pk_bf16_f32 v0, v7, s0
	v_lshl_add_u64 v[66:67], v[66:67], 0, s[8:9]
	global_store_short v[66:67], v0, off
	v_cvt_pk_bf16_f32 v0, v8, s0
	v_lshl_add_u64 v[66:67], v[66:67], 0, s[8:9]
	global_store_short v[66:67], v0, off
	v_cvt_pk_bf16_f32 v0, v9, s0
	v_lshl_add_u64 v[66:67], v[66:67], 0, s[8:9]
	global_store_short v[66:67], v0, off
	v_cvt_pk_bf16_f32 v0, v2, s0
	v_lshl_add_u64 v[66:67], v[66:67], 0, s[0:1]
	global_store_short v[66:67], v0, off
	v_cvt_pk_bf16_f32 v0, v3, s0
	v_lshl_add_u64 v[66:67], v[66:67], 0, s[8:9]
	global_store_short v[66:67], v0, off
	v_cvt_pk_bf16_f32 v0, v4, s0
	v_lshl_add_u64 v[66:67], v[66:67], 0, s[8:9]
	global_store_short v[66:67], v0, off
	v_cvt_pk_bf16_f32 v0, v5, s0
	v_lshl_add_u64 v[66:67], v[66:67], 0, s[8:9]
	global_store_short v[66:67], v0, off

.LBB0_1010:
	s_andn2_b64 vcc, exec, s[0:1]
	s_cbranch_vccnz .LBB0_1100
	s_movk_i32 s0, 0x2400
	v_cmp_gt_i32_e32 vcc, s0, v184
	s_and_saveexec_b64 s[0:1], vcc
	s_movk_i32 s33, 0x3ff
	s_cbranch_execz .LBB0_1018
	v_readlane_b32 s44, v253, 32
	v_readlane_b32 s45, v253, 33
	v_readlane_b32 s46, v253, 34
	v_readlane_b32 s47, v253, 35
	v_and_b32_e32 v0, 1, v184
	v_cmp_eq_u32_e32 vcc, 1, v0
	v_lshlrev_b32_e32 v2, 2, v184
	v_mov_b32_e32 v3, 0
	s_nop 0
	v_cndmask_b32_e64 v4, 0, 9, vcc
	v_lshl_add_u64 v[6:7], s[46:47], 0, v[2:3]
	global_load_dword v100, v[6:7], off
	v_lshl_add_u64 v[6:7], s[46:47], 0, v[2:3]
	global_load_dword v101, v[6:7], off offset:2048
	v_lshl_add_u64 v[6:7], s[44:45], 0, v[2:3]
	global_load_dword v102, v[6:7], off
	v_lshl_add_u64 v[6:7], s[44:45], 0, v[2:3]
	global_load_dword v103, v[6:7], off offset:2048
	v_lshl_add_u64 v[6:7], s[44:45], 0, v[2:3]
	s_mov_b64 s[22:23], 0x1000
	v_lshl_add_u64 v[6:7], v[6:7], 0, s[22:23]
	global_load_dword v104, v[6:7], off
	v_lshl_add_u64 v[6:7], s[44:45], 0, v[2:3]
	s_mov_b64 s[22:23], 0x1800
	v_lshl_add_u64 v[6:7], v[6:7], 0, s[22:23]
	global_load_dword v105, v[6:7], off
	v_lshl_add_u64 v[6:7], s[44:45], 0, v[2:3]
	s_mov_b64 s[22:23], 0x2000
	v_lshl_add_u64 v[6:7], v[6:7], 0, s[22:23]
	global_load_dword v106, v[6:7], off
	v_lshl_add_u64 v[6:7], s[44:45], 0, v[2:3]
	s_mov_b64 s[22:23], 0x2800
	v_lshl_add_u64 v[6:7], v[6:7], 0, s[22:23]
	global_load_dword v107, v[6:7], off
	v_lshl_add_u64 v[6:7], s[44:45], 0, v[2:3]
	s_mov_b64 s[22:23], 0x3000
	v_lshl_add_u64 v[6:7], v[6:7], 0, s[22:23]
	global_load_dword v108, v[6:7], off
	v_lshl_add_u64 v[6:7], s[44:45], 0, v[2:3]
	s_mov_b64 s[22:23], 0x3800
	v_lshl_add_u64 v[6:7], v[6:7], 0, s[22:23]
	global_load_dword v109, v[6:7], off
	v_lshl_add_u64 v[6:7], s[44:45], 0, v[2:3]
	s_mov_b64 s[22:23], 0x4000
	v_lshl_add_u64 v[6:7], v[6:7], 0, s[22:23]
	global_load_dword v110, v[6:7], off
	v_lshl_add_u64 v[6:7], s[44:45], 0, v[2:3]
	s_mov_b64 s[22:23], 0x4800
	v_lshl_add_u64 v[6:7], v[6:7], 0, s[22:23]
	global_load_dword v111, v[6:7], off
	v_lshl_add_u64 v[6:7], s[44:45], 0, v[2:3]
	s_mov_b64 s[22:23], 0x5000
	v_lshl_add_u64 v[6:7], v[6:7], 0, s[22:23]
	global_load_dword v112, v[6:7], off
	v_lshl_add_u64 v[6:7], s[44:45], 0, v[2:3]
	s_mov_b64 s[22:23], 0x5800
	v_lshl_add_u64 v[6:7], v[6:7], 0, s[22:23]
	global_load_dword v113, v[6:7], off
	v_lshl_add_u64 v[6:7], s[44:45], 0, v[2:3]
	s_mov_b64 s[22:23], 0x6000
	v_lshl_add_u64 v[6:7], v[6:7], 0, s[22:23]
	global_load_dword v114, v[6:7], off
	v_lshl_add_u64 v[6:7], s[44:45], 0, v[2:3]
	s_mov_b64 s[22:23], 0x6800
	v_lshl_add_u64 v[6:7], v[6:7], 0, s[22:23]
	global_load_dword v115, v[6:7], off
	v_lshl_add_u64 v[6:7], s[44:45], 0, v[2:3]
	s_mov_b64 s[22:23], 0x7000
	v_lshl_add_u64 v[6:7], v[6:7], 0, s[22:23]
	global_load_dword v116, v[6:7], off
	v_lshl_add_u64 v[6:7], s[44:45], 0, v[2:3]
	s_mov_b64 s[22:23], 0x7800
	v_lshl_add_u64 v[6:7], v[6:7], 0, s[22:23]
	global_load_dword v117, v[6:7], off
	v_lshlrev_b32_e32 v5, 1, v184
	v_and_b32_e32 v8, 0xfc, v5
	s_waitcnt vmcnt(0)
	v_add_u32_e32 v9, 0x0, v5
	v_and_b32_e32 v9, 0x700, v9
	v_add_u32_e32 v10, 0, v4
	v_lshl_add_u32 v10, v10, 11, 0
	v_add3_u32 v10, v10, v9, v8
	v_mul_f32_e32 v7, 0xbfb8aa3b, v100
	v_exp_f32_e32 v7, v7
	s_nop 0
	v_add_f32_e32 v7, 1.0, v7
	v_div_scale_f32 v11, s[24:25], v7, v7, v100
	v_rcp_f32_e32 v12, v11
	v_div_scale_f32 v6, vcc, v100, v7, v100
	v_fma_f32 v13, -v11, v12, 1.0
	v_fmac_f32_e32 v12, v13, v12
	v_mul_f32_e32 v13, v6, v12
	v_fma_f32 v16, -v11, v13, v6
	v_fmac_f32_e32 v13, v16, v12
	v_fma_f32 v6, -v11, v13, v6
	v_div_fmas_f32 v6, v6, v12, v13
	v_div_fixup_f32 v6, v6, v7, v100
	ds_write_b32 v10, v6
	v_add_u32_e32 v9, 0x400, v5
	v_and_b32_e32 v9, 0x700, v9
	v_add_u32_e32 v10, 0, v4
	v_lshl_add_u32 v10, v10, 11, 0
	v_add3_u32 v10, v10, v9, v8
	v_mul_f32_e32 v7, 0xbfb8aa3b, v101
	v_exp_f32_e32 v7, v7
	s_nop 0
	v_add_f32_e32 v7, 1.0, v7
	v_div_scale_f32 v11, s[24:25], v7, v7, v101
	v_rcp_f32_e32 v12, v11
	v_div_scale_f32 v6, vcc, v101, v7, v101
	v_fma_f32 v13, -v11, v12, 1.0
	v_fmac_f32_e32 v12, v13, v12
	v_mul_f32_e32 v13, v6, v12
	v_fma_f32 v16, -v11, v13, v6
	v_fmac_f32_e32 v13, v16, v12
	v_fma_f32 v6, -v11, v13, v6
	v_div_fmas_f32 v6, v6, v12, v13
	v_div_fixup_f32 v6, v6, v7, v101
	ds_write_b32 v10, v6
	v_add_u32_e32 v9, 0x0, v5
	v_and_b32_e32 v9, 0x700, v9
	v_add_u32_e32 v10, 1, v4
	v_lshl_add_u32 v10, v10, 11, 0
	v_add3_u32 v10, v10, v9, v8
	v_mul_f32_e32 v7, 0xbfb8aa3b, v102
	v_exp_f32_e32 v7, v7
	s_nop 0
	v_add_f32_e32 v7, 1.0, v7
	v_div_scale_f32 v11, s[24:25], v7, v7, v102
	v_rcp_f32_e32 v12, v11
	v_div_scale_f32 v6, vcc, v102, v7, v102
	v_fma_f32 v13, -v11, v12, 1.0
	v_fmac_f32_e32 v12, v13, v12
	v_mul_f32_e32 v13, v6, v12
	v_fma_f32 v16, -v11, v13, v6
	v_fmac_f32_e32 v13, v16, v12
	v_fma_f32 v6, -v11, v13, v6
	v_div_fmas_f32 v6, v6, v12, v13
	v_div_fixup_f32 v6, v6, v7, v102
	ds_write_b32 v10, v6
	v_add_u32_e32 v9, 0x400, v5
	v_and_b32_e32 v9, 0x700, v9
	v_add_u32_e32 v10, 1, v4
	v_lshl_add_u32 v10, v10, 11, 0
	v_add3_u32 v10, v10, v9, v8
	v_mul_f32_e32 v7, 0xbfb8aa3b, v103
	v_exp_f32_e32 v7, v7
	s_nop 0
	v_add_f32_e32 v7, 1.0, v7
	v_div_scale_f32 v11, s[24:25], v7, v7, v103
	v_rcp_f32_e32 v12, v11
	v_div_scale_f32 v6, vcc, v103, v7, v103
	v_fma_f32 v13, -v11, v12, 1.0
	v_fmac_f32_e32 v12, v13, v12
	v_mul_f32_e32 v13, v6, v12
	v_fma_f32 v16, -v11, v13, v6
	v_fmac_f32_e32 v13, v16, v12
	v_fma_f32 v6, -v11, v13, v6
	v_div_fmas_f32 v6, v6, v12, v13
	v_div_fixup_f32 v6, v6, v7, v103
	ds_write_b32 v10, v6
	v_add_u32_e32 v9, 0x0, v5
	v_and_b32_e32 v9, 0x700, v9
	v_add_u32_e32 v10, 2, v4
	v_lshl_add_u32 v10, v10, 11, 0
	v_add3_u32 v10, v10, v9, v8
	v_mul_f32_e32 v7, 0xbfb8aa3b, v104
	v_exp_f32_e32 v7, v7
	s_nop 0
	v_add_f32_e32 v7, 1.0, v7
	v_div_scale_f32 v11, s[24:25], v7, v7, v104
	v_rcp_f32_e32 v12, v11
	v_div_scale_f32 v6, vcc, v104, v7, v104
	v_fma_f32 v13, -v11, v12, 1.0
	v_fmac_f32_e32 v12, v13, v12
	v_mul_f32_e32 v13, v6, v12
	v_fma_f32 v16, -v11, v13, v6
	v_fmac_f32_e32 v13, v16, v12
	v_fma_f32 v6, -v11, v13, v6
	v_div_fmas_f32 v6, v6, v12, v13
	v_div_fixup_f32 v6, v6, v7, v104
	ds_write_b32 v10, v6
	v_add_u32_e32 v9, 0x400, v5
	v_and_b32_e32 v9, 0x700, v9
	v_add_u32_e32 v10, 2, v4
	v_lshl_add_u32 v10, v10, 11, 0
	v_add3_u32 v10, v10, v9, v8
	v_mul_f32_e32 v7, 0xbfb8aa3b, v105
	v_exp_f32_e32 v7, v7
	s_nop 0
	v_add_f32_e32 v7, 1.0, v7
	v_div_scale_f32 v11, s[24:25], v7, v7, v105
	v_rcp_f32_e32 v12, v11
	v_div_scale_f32 v6, vcc, v105, v7, v105
	v_fma_f32 v13, -v11, v12, 1.0
	v_fmac_f32_e32 v12, v13, v12
	v_mul_f32_e32 v13, v6, v12
	v_fma_f32 v16, -v11, v13, v6
	v_fmac_f32_e32 v13, v16, v12
	v_fma_f32 v6, -v11, v13, v6
	v_div_fmas_f32 v6, v6, v12, v13
	v_div_fixup_f32 v6, v6, v7, v105
	ds_write_b32 v10, v6
	v_add_u32_e32 v9, 0x0, v5
	v_and_b32_e32 v9, 0x700, v9
	v_add_u32_e32 v10, 3, v4
	v_lshl_add_u32 v10, v10, 11, 0
	v_add3_u32 v10, v10, v9, v8
	v_mul_f32_e32 v7, 0xbfb8aa3b, v106
	v_exp_f32_e32 v7, v7
	s_nop 0
	v_add_f32_e32 v7, 1.0, v7
	v_div_scale_f32 v11, s[24:25], v7, v7, v106
	v_rcp_f32_e32 v12, v11
	v_div_scale_f32 v6, vcc, v106, v7, v106
	v_fma_f32 v13, -v11, v12, 1.0
	v_fmac_f32_e32 v12, v13, v12
	v_mul_f32_e32 v13, v6, v12
	v_fma_f32 v16, -v11, v13, v6
	v_fmac_f32_e32 v13, v16, v12
	v_fma_f32 v6, -v11, v13, v6
	v_div_fmas_f32 v6, v6, v12, v13
	v_div_fixup_f32 v6, v6, v7, v106
	ds_write_b32 v10, v6
	v_add_u32_e32 v9, 0x400, v5
	v_and_b32_e32 v9, 0x700, v9
	v_add_u32_e32 v10, 3, v4
	v_lshl_add_u32 v10, v10, 11, 0
	v_add3_u32 v10, v10, v9, v8
	v_mul_f32_e32 v7, 0xbfb8aa3b, v107
	v_exp_f32_e32 v7, v7
	s_nop 0
	v_add_f32_e32 v7, 1.0, v7
	v_div_scale_f32 v11, s[24:25], v7, v7, v107
	v_rcp_f32_e32 v12, v11
	v_div_scale_f32 v6, vcc, v107, v7, v107
	v_fma_f32 v13, -v11, v12, 1.0
	v_fmac_f32_e32 v12, v13, v12
	v_mul_f32_e32 v13, v6, v12
	v_fma_f32 v16, -v11, v13, v6
	v_fmac_f32_e32 v13, v16, v12
	v_fma_f32 v6, -v11, v13, v6
	v_div_fmas_f32 v6, v6, v12, v13
	v_div_fixup_f32 v6, v6, v7, v107
	ds_write_b32 v10, v6
	v_add_u32_e32 v9, 0x0, v5
	v_and_b32_e32 v9, 0x700, v9
	v_add_u32_e32 v10, 4, v4
	v_lshl_add_u32 v10, v10, 11, 0
	v_add3_u32 v10, v10, v9, v8
	v_mul_f32_e32 v7, 0xbfb8aa3b, v108
	v_exp_f32_e32 v7, v7
	s_nop 0
	v_add_f32_e32 v7, 1.0, v7
	v_div_scale_f32 v11, s[24:25], v7, v7, v108
	v_rcp_f32_e32 v12, v11
	v_div_scale_f32 v6, vcc, v108, v7, v108
	v_fma_f32 v13, -v11, v12, 1.0
	v_fmac_f32_e32 v12, v13, v12
	v_mul_f32_e32 v13, v6, v12
	v_fma_f32 v16, -v11, v13, v6
	v_fmac_f32_e32 v13, v16, v12
	v_fma_f32 v6, -v11, v13, v6
	v_div_fmas_f32 v6, v6, v12, v13
	v_div_fixup_f32 v6, v6, v7, v108
	ds_write_b32 v10, v6
	v_add_u32_e32 v9, 0x400, v5
	v_and_b32_e32 v9, 0x700, v9
	v_add_u32_e32 v10, 4, v4
	v_lshl_add_u32 v10, v10, 11, 0
	v_add3_u32 v10, v10, v9, v8
	v_mul_f32_e32 v7, 0xbfb8aa3b, v109
	v_exp_f32_e32 v7, v7
	s_nop 0
	v_add_f32_e32 v7, 1.0, v7
	v_div_scale_f32 v11, s[24:25], v7, v7, v109
	v_rcp_f32_e32 v12, v11
	v_div_scale_f32 v6, vcc, v109, v7, v109
	v_fma_f32 v13, -v11, v12, 1.0
	v_fmac_f32_e32 v12, v13, v12
	v_mul_f32_e32 v13, v6, v12
	v_fma_f32 v16, -v11, v13, v6
	v_fmac_f32_e32 v13, v16, v12
	v_fma_f32 v6, -v11, v13, v6
	v_div_fmas_f32 v6, v6, v12, v13
	v_div_fixup_f32 v6, v6, v7, v109
	ds_write_b32 v10, v6
	v_add_u32_e32 v9, 0x0, v5
	v_and_b32_e32 v9, 0x700, v9
	v_add_u32_e32 v10, 5, v4
	v_lshl_add_u32 v10, v10, 11, 0
	v_add3_u32 v10, v10, v9, v8
	v_mul_f32_e32 v7, 0xbfb8aa3b, v110
	v_exp_f32_e32 v7, v7
	s_nop 0
	v_add_f32_e32 v7, 1.0, v7
	v_div_scale_f32 v11, s[24:25], v7, v7, v110
	v_rcp_f32_e32 v12, v11
	v_div_scale_f32 v6, vcc, v110, v7, v110
	v_fma_f32 v13, -v11, v12, 1.0
	v_fmac_f32_e32 v12, v13, v12
	v_mul_f32_e32 v13, v6, v12
	v_fma_f32 v16, -v11, v13, v6
	v_fmac_f32_e32 v13, v16, v12
	v_fma_f32 v6, -v11, v13, v6
	v_div_fmas_f32 v6, v6, v12, v13
	v_div_fixup_f32 v6, v6, v7, v110
	ds_write_b32 v10, v6
	v_add_u32_e32 v9, 0x400, v5
	v_and_b32_e32 v9, 0x700, v9
	v_add_u32_e32 v10, 5, v4
	v_lshl_add_u32 v10, v10, 11, 0
	v_add3_u32 v10, v10, v9, v8
	v_mul_f32_e32 v7, 0xbfb8aa3b, v111
	v_exp_f32_e32 v7, v7
	s_nop 0
	v_add_f32_e32 v7, 1.0, v7
	v_div_scale_f32 v11, s[24:25], v7, v7, v111
	v_rcp_f32_e32 v12, v11
	v_div_scale_f32 v6, vcc, v111, v7, v111
	v_fma_f32 v13, -v11, v12, 1.0
	v_fmac_f32_e32 v12, v13, v12
	v_mul_f32_e32 v13, v6, v12
	v_fma_f32 v16, -v11, v13, v6
	v_fmac_f32_e32 v13, v16, v12
	v_fma_f32 v6, -v11, v13, v6
	v_div_fmas_f32 v6, v6, v12, v13
	v_div_fixup_f32 v6, v6, v7, v111
	ds_write_b32 v10, v6
	v_add_u32_e32 v9, 0x0, v5
	v_and_b32_e32 v9, 0x700, v9
	v_add_u32_e32 v10, 6, v4
	v_lshl_add_u32 v10, v10, 11, 0
	v_add3_u32 v10, v10, v9, v8
	v_mul_f32_e32 v7, 0xbfb8aa3b, v112
	v_exp_f32_e32 v7, v7
	s_nop 0
	v_add_f32_e32 v7, 1.0, v7
	v_div_scale_f32 v11, s[24:25], v7, v7, v112
	v_rcp_f32_e32 v12, v11
	v_div_scale_f32 v6, vcc, v112, v7, v112
	v_fma_f32 v13, -v11, v12, 1.0
	v_fmac_f32_e32 v12, v13, v12
	v_mul_f32_e32 v13, v6, v12
	v_fma_f32 v16, -v11, v13, v6
	v_fmac_f32_e32 v13, v16, v12
	v_fma_f32 v6, -v11, v13, v6
	v_div_fmas_f32 v6, v6, v12, v13
	v_div_fixup_f32 v6, v6, v7, v112
	ds_write_b32 v10, v6
	v_add_u32_e32 v9, 0x400, v5
	v_and_b32_e32 v9, 0x700, v9
	v_add_u32_e32 v10, 6, v4
	v_lshl_add_u32 v10, v10, 11, 0
	v_add3_u32 v10, v10, v9, v8
	v_mul_f32_e32 v7, 0xbfb8aa3b, v113
	v_exp_f32_e32 v7, v7
	s_nop 0
	v_add_f32_e32 v7, 1.0, v7
	v_div_scale_f32 v11, s[24:25], v7, v7, v113
	v_rcp_f32_e32 v12, v11
	v_div_scale_f32 v6, vcc, v113, v7, v113
	v_fma_f32 v13, -v11, v12, 1.0
	v_fmac_f32_e32 v12, v13, v12
	v_mul_f32_e32 v13, v6, v12
	v_fma_f32 v16, -v11, v13, v6
	v_fmac_f32_e32 v13, v16, v12
	v_fma_f32 v6, -v11, v13, v6
	v_div_fmas_f32 v6, v6, v12, v13
	v_div_fixup_f32 v6, v6, v7, v113
	ds_write_b32 v10, v6
	v_add_u32_e32 v9, 0x0, v5
	v_and_b32_e32 v9, 0x700, v9
	v_add_u32_e32 v10, 7, v4
	v_lshl_add_u32 v10, v10, 11, 0
	v_add3_u32 v10, v10, v9, v8
	v_mul_f32_e32 v7, 0xbfb8aa3b, v114
	v_exp_f32_e32 v7, v7
	s_nop 0
	v_add_f32_e32 v7, 1.0, v7
	v_div_scale_f32 v11, s[24:25], v7, v7, v114
	v_rcp_f32_e32 v12, v11
	v_div_scale_f32 v6, vcc, v114, v7, v114
	v_fma_f32 v13, -v11, v12, 1.0
	v_fmac_f32_e32 v12, v13, v12
	v_mul_f32_e32 v13, v6, v12
	v_fma_f32 v16, -v11, v13, v6
	v_fmac_f32_e32 v13, v16, v12
	v_fma_f32 v6, -v11, v13, v6
	v_div_fmas_f32 v6, v6, v12, v13
	v_div_fixup_f32 v6, v6, v7, v114
	ds_write_b32 v10, v6
	v_add_u32_e32 v9, 0x400, v5
	v_and_b32_e32 v9, 0x700, v9
	v_add_u32_e32 v10, 7, v4
	v_lshl_add_u32 v10, v10, 11, 0
	v_add3_u32 v10, v10, v9, v8
	v_mul_f32_e32 v7, 0xbfb8aa3b, v115
	v_exp_f32_e32 v7, v7
	s_nop 0
	v_add_f32_e32 v7, 1.0, v7
	v_div_scale_f32 v11, s[24:25], v7, v7, v115
	v_rcp_f32_e32 v12, v11
	v_div_scale_f32 v6, vcc, v115, v7, v115
	v_fma_f32 v13, -v11, v12, 1.0
	v_fmac_f32_e32 v12, v13, v12
	v_mul_f32_e32 v13, v6, v12
	v_fma_f32 v16, -v11, v13, v6
	v_fmac_f32_e32 v13, v16, v12
	v_fma_f32 v6, -v11, v13, v6
	v_div_fmas_f32 v6, v6, v12, v13
	v_div_fixup_f32 v6, v6, v7, v115
	ds_write_b32 v10, v6
	v_add_u32_e32 v9, 0x0, v5
	v_and_b32_e32 v9, 0x700, v9
	v_add_u32_e32 v10, 8, v4
	v_lshl_add_u32 v10, v10, 11, 0
	v_add3_u32 v10, v10, v9, v8
	v_mul_f32_e32 v7, 0xbfb8aa3b, v116
	v_exp_f32_e32 v7, v7
	s_nop 0
	v_add_f32_e32 v7, 1.0, v7
	v_div_scale_f32 v11, s[24:25], v7, v7, v116
	v_rcp_f32_e32 v12, v11
	v_div_scale_f32 v6, vcc, v116, v7, v116
	v_fma_f32 v13, -v11, v12, 1.0
	v_fmac_f32_e32 v12, v13, v12
	v_mul_f32_e32 v13, v6, v12
	v_fma_f32 v16, -v11, v13, v6
	v_fmac_f32_e32 v13, v16, v12
	v_fma_f32 v6, -v11, v13, v6
	v_div_fmas_f32 v6, v6, v12, v13
	v_div_fixup_f32 v6, v6, v7, v116
	ds_write_b32 v10, v6
	v_add_u32_e32 v9, 0x400, v5
	v_and_b32_e32 v9, 0x700, v9
	v_add_u32_e32 v10, 8, v4
	v_lshl_add_u32 v10, v10, 11, 0
	v_add3_u32 v10, v10, v9, v8
	v_mul_f32_e32 v7, 0xbfb8aa3b, v117
	v_exp_f32_e32 v7, v7
	s_nop 0
	v_add_f32_e32 v7, 1.0, v7
	v_div_scale_f32 v11, s[24:25], v7, v7, v117
	v_rcp_f32_e32 v12, v11
	v_div_scale_f32 v6, vcc, v117, v7, v117
	v_fma_f32 v13, -v11, v12, 1.0
	v_fmac_f32_e32 v12, v13, v12
	v_mul_f32_e32 v13, v6, v12
	v_fma_f32 v16, -v11, v13, v6
	v_fmac_f32_e32 v13, v16, v12
	v_fma_f32 v6, -v11, v13, v6
	v_div_fmas_f32 v6, v6, v12, v13
	v_div_fixup_f32 v6, v6, v7, v117
	ds_write_b32 v10, v6

.LBB0_1096:
	global_load_dwordx4 v[6:9], v[2:3], off offset:-16
	global_load_dwordx4 v[10:13], v[2:3], off
	v_ashrrev_i32_e32 v0, 5, v4
	v_mov_b64_e32 v[14:15], s[96:97]
	v_and_b32_e32 v5, 0xf8, v22
	v_add_u32_e32 v4, s64, v4
	v_lshrrev_b32_e32 v16, 2, v0
	v_and_b32_e32 v17, 3, v0
	v_lshlrev_b32_e32 v16, 11, v16
	v_lshl_or_b32 v16, v17, 4, v16
	v_mov_b32_e32 v17, 0
	v_lshl_add_u64 v[14:15], v[14:15], 0, v[16:17]
	v_lshlrev_b32_e32 v0, 3, v5
	v_cmp_lt_i32_e32 vcc, s78, v4
	v_lshl_add_u64 v[2:3], v[2:3], 0, s[80:81]
	v_add_u32_e32 v22, s13, v22
	v_lshl_add_u64 v[14:15], v[14:15], 0, v[0:1]
	s_or_b64 s[22:23], vcc, s[22:23]
	s_waitcnt vmcnt(1)
	v_cvt_pk_bf16_f32 v6, v6, v7
	v_cvt_pk_bf16_f32 v7, v8, v9
	s_waitcnt vmcnt(0)
	v_cvt_pk_bf16_f32 v8, v10, v11
	v_cvt_pk_bf16_f32 v9, v12, v13
	global_store_dwordx4 v[14:15], v[6:9], off
	s_andn2_b64 exec, exec, s[22:23]
	s_cbranch_execnz .LBB0_1096
	s_or_b64 exec, exec, s[22:23]
	v_readlane_b32 s36, v253, 24
	v_lshlrev_b32_e32 v0, 2, v182
	v_readlane_b32 s42, v253, 30
	v_readlane_b32 s43, v253, 31
	s_mov_b64 s[22:23], 0
	s_mov_b32 s3, 0xf800000
	v_lshl_add_u64 v[2:3], s[42:43], 0, v[0:1]
	v_readlane_b32 s37, v253, 25
	v_readlane_b32 s38, v253, 26
	v_readlane_b32 s39, v253, 27
	v_readlane_b32 s40, v253, 28
	v_readlane_b32 s41, v253, 29
	v_readlane_b32 s44, v253, 32
	v_readlane_b32 s45, v253, 33
	v_readlane_b32 s46, v253, 34
	v_readlane_b32 s47, v253, 35
	v_readlane_b32 s48, v253, 36
	v_readlane_b32 s49, v253, 37
	v_readlane_b32 s50, v253, 38
	v_readlane_b32 s51, v253, 39
.LBB0_1098:
	v_ashrrev_i32_e32 v23, 14, v180
	v_lshrrev_b32_e32 v0, 3, v180
	v_lshrrev_b32_e32 v4, 4, v180
	v_and_b32_e32 v5, 0x1f0, v0
	v_and_b32_e32 v4, 4, v4
	v_lshlrev_b32_e32 v6, 9, v23
	v_or3_b32 v4, v4, v6, v5
	v_bfe_u32 v22, v180, 12, 2
	v_or_b32_e32 v8, 1, v4
	v_or_b32_e32 v10, 2, v4
	v_or_b32_e32 v12, 3, v4
	v_or_b32_e32 v14, 8, v4
	v_or_b32_e32 v16, 9, v4
	v_or_b32_e32 v18, 10, v4
	v_or_b32_e32 v20, 11, v4
	v_lshlrev_b32_e32 v0, 8, v22
	v_ashrrev_i32_e32 v5, 31, v4
	v_ashrrev_i32_e32 v9, 31, v8
	v_ashrrev_i32_e32 v11, 31, v10
	v_ashrrev_i32_e32 v13, 31, v12
	v_ashrrev_i32_e32 v15, 31, v14
	v_ashrrev_i32_e32 v17, 31, v16
	v_ashrrev_i32_e32 v19, 31, v18
	v_ashrrev_i32_e32 v21, 31, v20
	v_lshl_add_u64 v[6:7], v[2:3], 0, v[0:1]
	v_lshlrev_b64 v[4:5], 10, v[4:5]
	v_lshlrev_b64 v[8:9], 10, v[8:9]
	v_lshlrev_b64 v[10:11], 10, v[10:11]
	v_lshlrev_b64 v[12:13], 10, v[12:13]
	v_lshlrev_b64 v[14:15], 10, v[14:15]
	v_lshlrev_b64 v[16:17], 10, v[16:17]
	v_lshlrev_b64 v[18:19], 10, v[18:19]
	v_lshlrev_b64 v[20:21], 10, v[20:21]
	v_lshl_add_u64 v[4:5], v[6:7], 0, v[4:5]
	v_lshl_add_u64 v[8:9], v[6:7], 0, v[8:9]
	v_lshl_add_u64 v[10:11], v[6:7], 0, v[10:11]
	v_lshl_add_u64 v[12:13], v[6:7], 0, v[12:13]
	v_lshl_add_u64 v[14:15], v[6:7], 0, v[14:15]
	v_lshl_add_u64 v[16:17], v[6:7], 0, v[16:17]
	v_lshl_add_u64 v[18:19], v[6:7], 0, v[18:19]
	v_lshl_add_u64 v[6:7], v[6:7], 0, v[20:21]
	global_load_dword v20, v[4:5], off
	global_load_dword v21, v[8:9], off
	s_nop 0
	global_load_dword v10, v[10:11], off
	s_nop 0
	global_load_dword v11, v[12:13], off
	s_nop 0
	global_load_dword v12, v[14:15], off
	global_load_dword v13, v[16:17], off
	s_nop 0
	global_load_dword v14, v[18:19], off
	s_nop 0
	global_load_dword v7, v[6:7], off
	v_lshlrev_b32_e32 v6, 6, v22
	v_lshlrev_b32_e32 v8, 18, v23
	v_mov_b64_e32 v[4:5], s[74:75]
	v_lshrrev_b32_e32 v0, 2, v180
	v_add_u32_e32 v180, s64, v180
	v_or_b32_e32 v6, v6, v182
	s_movk_i32 s8, 32
	v_cmp_lt_i32_e32 vcc, s78, v180
	v_and_b32_e32 v0, 0x3f0, v0
	v_mad_i64_i32 v[4:5], s[24:25], v6, s8, v[4:5]
	s_or_b64 s[22:23], vcc, s[22:23]
	v_lshrrev_b32_e32 v6, 5, v0
	v_and_b32_e32 v0, 16, v0
	v_lshl_or_b32 v0, v6, 13, v0
	v_or_b32_e32 v0, v0, v8
	v_lshl_add_u64 v[8:9], v[4:5], 0, v[0:1]
	s_waitcnt vmcnt(6)
	v_cvt_pk_bf16_f32 v4, v20, v21
	s_waitcnt vmcnt(4)
	v_cvt_pk_bf16_f32 v5, v10, v11
	s_waitcnt vmcnt(2)
	v_cvt_pk_bf16_f32 v6, v12, v13
	s_waitcnt vmcnt(0)
	v_cvt_pk_bf16_f32 v7, v14, v7
	global_store_dwordx4 v[8:9], v[4:7], off
	s_andn2_b64 exec, exec, s[22:23]
	s_cbranch_execnz .LBB0_1098
